# OUTNORM_C fused into the scan phases: the barrier-matching half-block of each scan workgroup applies the gated per-head rmsnorm to the previous chunk; the OUTNORM_C phase does nothing
# speedup vs baseline: 1.0017x; 1.0017x over previous
; DI float shx(float v, int m) { return __int_as_float(__builtin_amdgcn_ds_bpermute((lane_now() ^ m) << 2, __float_as_int(v))); }
; DI int shx(int v, int m) { return __builtin_amdgcn_ds_bpermute((lane_now() ^ m) << 2, v); }
; DI u16 f2bf(float x) { return (u16)(pk2bf(x, 0.f) & 0xffffu); }
; DI float bfs(short v) { return __uint_as_float(((unsigned)(u16)v) << 16); }
; DI void phase_scan_c(int wv_, int vb_, int nvb_, char* ws_, const Ctx& p, char* smem, int half) {
;     ...
;   if ((vb_ >> 1) < 64 && (vb_ & 1)) { for (int q_ = 0; q_ < 66; ++q_) __syncthreads(); }
; DI void phase_outnorm_c(int wv_, int vb_, int nvb_, char* ws_, const Ctx& p) {
;   u16* O = (u16*)(ws_ + WS_H); const u16* G = (const u16*)(ws_ + WS_CG);
;   const int tid = tidx(wv_); const int e = tid & 15;
;   float og[8];
; #pragma unroll
;   for (int j = 0; j < 8; ++j) og[j] = p.c_o_gain[e * 8 + j];
;   const size_t stride = (size_t)nvb_ * 256, total = (size_t)NTOK * 8 * 16;
;   for (size_t idx0 = (size_t)vb_ * 256 + tid; idx0 < total; idx0 += 4 * stride) {
;     bf16x8 ov[4], gv[4]; bool ok[4];
; #pragma unroll
;     for (int q = 0; q < 4; ++q) { const size_t idx = idx0 + q * stride; ok[q] = idx < total; const size_t rowh = (ok[q] ? idx : idx0) >> 4;
;       ov[q] = *(const bf16x8*)(O + rowh * 128 + e * 8); gv[q] = *(const bf16x8*)(G + rowh * 128 + e * 8); }
; #pragma unroll
;     for (int q = 0; q < 4; ++q) {
;       float f[8]; float ss = 0.f;
; #pragma unroll
;       for (int j = 0; j < 8; ++j) { f[j] = bfs(ov[q][j]); ss += f[j] * f[j]; }
;       ss += shx(ss, 1); ss += shx(ss, 2); ss += shx(ss, 4); ss += shx(ss, 8);
;       const float rn = rsqrtf(ss * (1.0f / 128.0f) + 1e-6f);
;       bf16x8 o;
; #pragma unroll
;       for (int j = 0; j < 8; ++j) { float gt = bfs(gv[q][j]); float sl = gt * __builtin_amdgcn_rcpf(1.0f + __expf(-gt)); o[j] = (short)f2bf(f[j] * rn * og[j] * sl); }
;       if (ok[q]) *(bf16x8*)(O + ((idx0 + q * stride) >> 4) * 128 + e * 8) = o;
;     }
;   }
.LBB0_161:
	s_and_b64 vcc, exec, s[2:3]
	s_cbranch_vccz .LBB0_169
	v_readlane_b32 s2, v252, 13
	v_readlane_b32 s3, v252, 14
	s_mov_b32 s0, s33
	v_mov_b32_e32 v2, v204
	s_andn2_b64 vcc, exec, s[2:3]
	s_cbranch_vccnz .LBB0_165
	v_lshl_or_b32 v10, s33, 6, v204
	v_and_b32_e32 v11, 15, v10
	v_lshrrev_b32_e32 v12, 4, v10
	v_readlane_b32 s2, v254, 14
	s_lshr_b32 s2, s2, 1
	s_and_b32 s3, s2, 7
	s_lshr_b32 s2, s2, 3
	s_lshl_b32 s2, s2, 12
	s_lshl_b32 s2, s2, 3
	s_add_i32 s2, s2, s3
	s_lshl_b32 s2, s2, 8
	v_lshlrev_b32_e32 v13, 11, v12
	v_lshl_add_u32 v13, v11, 4, v13
	v_add_u32_e32 v13, s2, v13
	s_add_u32 s6, s78, 0x19600000
	s_addc_u32 s7, s79, 0
	s_mov_b64 s[4:5], s[82:83]
	v_readlane_b32 s8, v254, 28
	v_readlane_b32 s9, v254, 29
	v_lshlrev_b32_e32 v14, 5, v11
	s_nop 3
	global_load_dwordx4 v[2:5], v14, s[8:9]
	global_load_dwordx4 v[6:9], v14, s[8:9] offset:16
	s_waitcnt vmcnt(0)
	s_barrier
	s_barrier
	s_mov_b32 s10, 0
.Long_loop:
	s_barrier
	s_cmp_eq_u32 s10, 0
	s_cbranch_scc1 .Long_noproc
	s_mov_b64 s[12:13], s[4:5]
	s_mov_b64 s[14:15], s[6:7]
	global_load_dwordx4 v[16:19], v13, s[12:13]
	global_load_dwordx4 v[32:35], v13, s[14:15]
	s_add_u32 s12, s12, 0x8000
	s_addc_u32 s13, s13, 0
	s_add_u32 s14, s14, 0x8000
	s_addc_u32 s15, s15, 0
	global_load_dwordx4 v[20:23], v13, s[12:13]
	global_load_dwordx4 v[36:39], v13, s[14:15]
	s_add_u32 s12, s12, 0x8000
	s_addc_u32 s13, s13, 0
	s_add_u32 s14, s14, 0x8000
	s_addc_u32 s15, s15, 0
	global_load_dwordx4 v[24:27], v13, s[12:13]
	global_load_dwordx4 v[40:43], v13, s[14:15]
	s_add_u32 s12, s12, 0x8000
	s_addc_u32 s13, s13, 0
	s_add_u32 s14, s14, 0x8000
	s_addc_u32 s15, s15, 0
	global_load_dwordx4 v[28:31], v13, s[12:13]
	global_load_dwordx4 v[44:47], v13, s[14:15]
	s_mov_b64 s[12:13], s[4:5]
	s_waitcnt vmcnt(6)
	v_lshlrev_b32_e32 v48, 16, v16
	v_and_b32_e32 v49, 0xffff0000, v16
	v_lshlrev_b32_e32 v50, 16, v17
	v_and_b32_e32 v51, 0xffff0000, v17
	v_lshlrev_b32_e32 v52, 16, v18
	v_and_b32_e32 v53, 0xffff0000, v18
	v_lshlrev_b32_e32 v54, 16, v19
	v_and_b32_e32 v55, 0xffff0000, v19
	v_mul_f32_e32 v56, v48, v48
	v_mul_f32_e32 v57, v49, v49
	v_add_f32_e32 v56, v56, v57
	v_mul_f32_e32 v57, v50, v50
	v_add_f32_e32 v56, v57, v56
	v_mul_f32_e32 v57, v51, v51
	v_add_f32_e32 v56, v57, v56
	v_mul_f32_e32 v57, v52, v52
	v_add_f32_e32 v56, v57, v56
	v_mul_f32_e32 v57, v53, v53
	v_add_f32_e32 v56, v57, v56
	v_mul_f32_e32 v57, v54, v54
	v_add_f32_e32 v56, v57, v56
	v_mul_f32_e32 v57, v55, v55
	v_add_f32_e32 v56, v57, v56
	s_nop 1
	v_add_f32_dpp v56, v56, v56 quad_perm:[1,0,3,2] row_mask:0xf bank_mask:0xf
	s_nop 1
	v_add_f32_dpp v56, v56, v56 quad_perm:[2,3,0,1] row_mask:0xf bank_mask:0xf
	s_nop 1
	v_add_f32_dpp v56, v56, v56 row_half_mirror row_mask:0xf bank_mask:0xf
	s_nop 1
	v_add_f32_dpp v56, v56, v56 row_mirror row_mask:0xf bank_mask:0xf
	v_fmamk_f32 v56, v56, 0x3c000000, v206
	v_mul_f32_e32 v57, 0x4b800000, v56
	v_cmp_gt_f32_e32 vcc, s51, v56
	s_nop 1
	v_cndmask_b32_e32 v56, v56, v57, vcc
	v_rsq_f32_e32 v56, v56
	s_nop 0
	v_mul_f32_e32 v57, 0x45800000, v56
	v_cndmask_b32_e32 v56, v56, v57, vcc
	v_lshlrev_b32_e32 v58, 16, v32
	v_and_b32_e32 v59, 0xffff0000, v32
	v_lshlrev_b32_e32 v60, 16, v33
	v_and_b32_e32 v61, 0xffff0000, v33
	v_lshlrev_b32_e32 v62, 16, v34
	v_and_b32_e32 v63, 0xffff0000, v34
	v_lshlrev_b32_e32 v64, 16, v35
	v_and_b32_e32 v65, 0xffff0000, v35
	v_mul_f32_e32 v66, 0xbfb8aa3b, v58
	v_mul_f32_e32 v67, 0xbfb8aa3b, v59
	v_mul_f32_e32 v68, 0xbfb8aa3b, v60
	v_mul_f32_e32 v69, 0xbfb8aa3b, v61
	v_mul_f32_e32 v70, 0xbfb8aa3b, v62
	v_mul_f32_e32 v71, 0xbfb8aa3b, v63
	v_mul_f32_e32 v72, 0xbfb8aa3b, v64
	v_mul_f32_e32 v73, 0xbfb8aa3b, v65
	v_exp_f32_e32 v66, v66
	v_exp_f32_e32 v67, v67
	v_exp_f32_e32 v68, v68
	v_exp_f32_e32 v69, v69
	v_exp_f32_e32 v70, v70
	v_exp_f32_e32 v71, v71
	v_exp_f32_e32 v72, v72
	v_exp_f32_e32 v73, v73
	v_add_f32_e32 v66, 1.0, v66
	v_add_f32_e32 v67, 1.0, v67
	v_add_f32_e32 v68, 1.0, v68
	v_add_f32_e32 v69, 1.0, v69
	v_add_f32_e32 v70, 1.0, v70
	v_add_f32_e32 v71, 1.0, v71
	v_add_f32_e32 v72, 1.0, v72
	v_add_f32_e32 v73, 1.0, v73
	v_rcp_f32_e32 v66, v66
	v_rcp_f32_e32 v67, v67
	v_rcp_f32_e32 v68, v68
	v_rcp_f32_e32 v69, v69
	v_rcp_f32_e32 v70, v70
	v_rcp_f32_e32 v71, v71
	v_rcp_f32_e32 v72, v72
	v_rcp_f32_e32 v73, v73
	v_mul_f32_e32 v66, v66, v58
	v_mul_f32_e32 v67, v67, v59
	v_mul_f32_e32 v68, v68, v60
	v_mul_f32_e32 v69, v69, v61
	v_mul_f32_e32 v70, v70, v62
	v_mul_f32_e32 v71, v71, v63
	v_mul_f32_e32 v72, v72, v64
	v_mul_f32_e32 v73, v73, v65
	v_mul_f32_e32 v48, v56, v48
	v_mul_f32_e32 v49, v56, v49
	v_mul_f32_e32 v50, v56, v50
	v_mul_f32_e32 v51, v56, v51
	v_mul_f32_e32 v52, v56, v52
	v_mul_f32_e32 v53, v56, v53
	v_mul_f32_e32 v54, v56, v54
	v_mul_f32_e32 v55, v56, v55
	v_mul_f32_e32 v48, v2, v48
	v_mul_f32_e32 v49, v3, v49
	v_mul_f32_e32 v50, v4, v50
	v_mul_f32_e32 v51, v5, v51
	v_mul_f32_e32 v52, v6, v52
	v_mul_f32_e32 v53, v7, v53
	v_mul_f32_e32 v54, v8, v54
	v_mul_f32_e32 v55, v9, v55
	v_mul_f32_e32 v48, v66, v48
	v_mul_f32_e32 v49, v67, v49
	v_mul_f32_e32 v50, v68, v50
	v_mul_f32_e32 v51, v69, v51
	v_mul_f32_e32 v52, v70, v52
	v_mul_f32_e32 v53, v71, v53
	v_mul_f32_e32 v54, v72, v54
	v_mul_f32_e32 v55, v73, v55
	v_cvt_pk_bf16_f32 v16, v48, v49
	v_cvt_pk_bf16_f32 v17, v50, v51
	v_cvt_pk_bf16_f32 v18, v52, v53
	v_cvt_pk_bf16_f32 v19, v54, v55
	global_store_dwordx4 v13, v[16:19], s[12:13]
	s_waitcnt vmcnt(5)
; DI float shx(float v, int m) { return __int_as_float(__builtin_amdgcn_ds_bpermute((lane_now() ^ m) << 2, __float_as_int(v))); }
; DI int shx(int v, int m) { return __builtin_amdgcn_ds_bpermute((lane_now() ^ m) << 2, v); }
; DI u16 f2bf(float x) { return (u16)(pk2bf(x, 0.f) & 0xffffu); }
; DI float bfs(short v) { return __uint_as_float(((unsigned)(u16)v) << 16); }
; DI void phase_outnorm_c(int wv_, int vb_, int nvb_, char* ws_, const Ctx& p) {
;     ...
;     for (int q = 0; q < 4; ++q) {
;       float f[8]; float ss = 0.f;
; #pragma unroll
;       for (int j = 0; j < 8; ++j) { f[j] = bfs(ov[q][j]); ss += f[j] * f[j]; }
;       ss += shx(ss, 1); ss += shx(ss, 2); ss += shx(ss, 4); ss += shx(ss, 8);
;       const float rn = rsqrtf(ss * (1.0f / 128.0f) + 1e-6f);
;       bf16x8 o;
; #pragma unroll
;       for (int j = 0; j < 8; ++j) { float gt = bfs(gv[q][j]); float sl = gt * __builtin_amdgcn_rcpf(1.0f + __expf(-gt)); o[j] = (short)f2bf(f[j] * rn * og[j] * sl); }
;       if (ok[q]) *(bf16x8*)(O + ((idx0 + q * stride) >> 4) * 128 + e * 8) = o;
	v_lshlrev_b32_e32 v48, 16, v20
	v_and_b32_e32 v49, 0xffff0000, v20
	v_lshlrev_b32_e32 v50, 16, v21
	v_and_b32_e32 v51, 0xffff0000, v21
	v_lshlrev_b32_e32 v52, 16, v22
	v_and_b32_e32 v53, 0xffff0000, v22
	v_lshlrev_b32_e32 v54, 16, v23
	v_and_b32_e32 v55, 0xffff0000, v23
	v_mul_f32_e32 v56, v48, v48
	v_mul_f32_e32 v57, v49, v49
	v_add_f32_e32 v56, v56, v57
	v_mul_f32_e32 v57, v50, v50
	v_add_f32_e32 v56, v57, v56
	v_mul_f32_e32 v57, v51, v51
	v_add_f32_e32 v56, v57, v56
	v_mul_f32_e32 v57, v52, v52
	v_add_f32_e32 v56, v57, v56
	v_mul_f32_e32 v57, v53, v53
	v_add_f32_e32 v56, v57, v56
	v_mul_f32_e32 v57, v54, v54
	v_add_f32_e32 v56, v57, v56
	v_mul_f32_e32 v57, v55, v55
	v_add_f32_e32 v56, v57, v56
	s_nop 1
	v_add_f32_dpp v56, v56, v56 quad_perm:[1,0,3,2] row_mask:0xf bank_mask:0xf
	s_nop 1
	v_add_f32_dpp v56, v56, v56 quad_perm:[2,3,0,1] row_mask:0xf bank_mask:0xf
	s_nop 1
	v_add_f32_dpp v56, v56, v56 row_half_mirror row_mask:0xf bank_mask:0xf
	s_nop 1
	v_add_f32_dpp v56, v56, v56 row_mirror row_mask:0xf bank_mask:0xf
	v_fmamk_f32 v56, v56, 0x3c000000, v206
	v_mul_f32_e32 v57, 0x4b800000, v56
	v_cmp_gt_f32_e32 vcc, s51, v56
	s_nop 1
	v_cndmask_b32_e32 v56, v56, v57, vcc
	v_rsq_f32_e32 v56, v56
	s_nop 0
	v_mul_f32_e32 v57, 0x45800000, v56
	v_cndmask_b32_e32 v56, v56, v57, vcc
	v_lshlrev_b32_e32 v58, 16, v36
	v_and_b32_e32 v59, 0xffff0000, v36
	v_lshlrev_b32_e32 v60, 16, v37
	v_and_b32_e32 v61, 0xffff0000, v37
	v_lshlrev_b32_e32 v62, 16, v38
	v_and_b32_e32 v63, 0xffff0000, v38
	v_lshlrev_b32_e32 v64, 16, v39
	v_and_b32_e32 v65, 0xffff0000, v39
	v_mul_f32_e32 v66, 0xbfb8aa3b, v58
	v_mul_f32_e32 v67, 0xbfb8aa3b, v59
	v_mul_f32_e32 v68, 0xbfb8aa3b, v60
	v_mul_f32_e32 v69, 0xbfb8aa3b, v61
	v_mul_f32_e32 v70, 0xbfb8aa3b, v62
	v_mul_f32_e32 v71, 0xbfb8aa3b, v63
	v_mul_f32_e32 v72, 0xbfb8aa3b, v64
	v_mul_f32_e32 v73, 0xbfb8aa3b, v65
	v_exp_f32_e32 v66, v66
	v_exp_f32_e32 v67, v67
	v_exp_f32_e32 v68, v68
	v_exp_f32_e32 v69, v69
	v_exp_f32_e32 v70, v70
	v_exp_f32_e32 v71, v71
	v_exp_f32_e32 v72, v72
	v_exp_f32_e32 v73, v73
	v_add_f32_e32 v66, 1.0, v66
	v_add_f32_e32 v67, 1.0, v67
	v_add_f32_e32 v68, 1.0, v68
	v_add_f32_e32 v69, 1.0, v69
	v_add_f32_e32 v70, 1.0, v70
	v_add_f32_e32 v71, 1.0, v71
	v_add_f32_e32 v72, 1.0, v72
	v_add_f32_e32 v73, 1.0, v73
	v_rcp_f32_e32 v66, v66
	v_rcp_f32_e32 v67, v67
	v_rcp_f32_e32 v68, v68
	v_rcp_f32_e32 v69, v69
	v_rcp_f32_e32 v70, v70
	v_rcp_f32_e32 v71, v71
	v_rcp_f32_e32 v72, v72
	v_rcp_f32_e32 v73, v73
	v_mul_f32_e32 v66, v66, v58
	v_mul_f32_e32 v67, v67, v59
	v_mul_f32_e32 v68, v68, v60
	v_mul_f32_e32 v69, v69, v61
	v_mul_f32_e32 v70, v70, v62
	v_mul_f32_e32 v71, v71, v63
	v_mul_f32_e32 v72, v72, v64
	v_mul_f32_e32 v73, v73, v65
	v_mul_f32_e32 v48, v56, v48
	v_mul_f32_e32 v49, v56, v49
	v_mul_f32_e32 v50, v56, v50
	v_mul_f32_e32 v51, v56, v51
	v_mul_f32_e32 v52, v56, v52
	v_mul_f32_e32 v53, v56, v53
	v_mul_f32_e32 v54, v56, v54
	v_mul_f32_e32 v55, v56, v55
	v_mul_f32_e32 v48, v2, v48
	v_mul_f32_e32 v49, v3, v49
	v_mul_f32_e32 v50, v4, v50
	v_mul_f32_e32 v51, v5, v51
	v_mul_f32_e32 v52, v6, v52
	v_mul_f32_e32 v53, v7, v53
	v_mul_f32_e32 v54, v8, v54
	v_mul_f32_e32 v55, v9, v55
	v_mul_f32_e32 v48, v66, v48
	v_mul_f32_e32 v49, v67, v49
	v_mul_f32_e32 v50, v68, v50
	v_mul_f32_e32 v51, v69, v51
	v_mul_f32_e32 v52, v70, v52
	v_mul_f32_e32 v53, v71, v53
	v_mul_f32_e32 v54, v72, v54
	v_mul_f32_e32 v55, v73, v55
	v_cvt_pk_bf16_f32 v20, v48, v49
	v_cvt_pk_bf16_f32 v21, v50, v51
	v_cvt_pk_bf16_f32 v22, v52, v53
	v_cvt_pk_bf16_f32 v23, v54, v55
	s_add_u32 s12, s12, 0x8000
	s_addc_u32 s13, s13, 0
	global_store_dwordx4 v13, v[20:23], s[12:13]
	s_waitcnt vmcnt(4)
	v_lshlrev_b32_e32 v48, 16, v24
	v_and_b32_e32 v49, 0xffff0000, v24
	v_lshlrev_b32_e32 v50, 16, v25
	v_and_b32_e32 v51, 0xffff0000, v25
	v_lshlrev_b32_e32 v52, 16, v26
	v_and_b32_e32 v53, 0xffff0000, v26
	v_lshlrev_b32_e32 v54, 16, v27
	v_and_b32_e32 v55, 0xffff0000, v27
	v_mul_f32_e32 v56, v48, v48
	v_mul_f32_e32 v57, v49, v49
	v_add_f32_e32 v56, v56, v57
	v_mul_f32_e32 v57, v50, v50
	v_add_f32_e32 v56, v57, v56
	v_mul_f32_e32 v57, v51, v51
	v_add_f32_e32 v56, v57, v56
	v_mul_f32_e32 v57, v52, v52
	v_add_f32_e32 v56, v57, v56
	v_mul_f32_e32 v57, v53, v53
	v_add_f32_e32 v56, v57, v56
	v_mul_f32_e32 v57, v54, v54
	v_add_f32_e32 v56, v57, v56
	v_mul_f32_e32 v57, v55, v55
	v_add_f32_e32 v56, v57, v56
	s_nop 1
	v_add_f32_dpp v56, v56, v56 quad_perm:[1,0,3,2] row_mask:0xf bank_mask:0xf
	s_nop 1
	v_add_f32_dpp v56, v56, v56 quad_perm:[2,3,0,1] row_mask:0xf bank_mask:0xf
	s_nop 1
	v_add_f32_dpp v56, v56, v56 row_half_mirror row_mask:0xf bank_mask:0xf
	s_nop 1
	v_add_f32_dpp v56, v56, v56 row_mirror row_mask:0xf bank_mask:0xf
	v_fmamk_f32 v56, v56, 0x3c000000, v206
	v_mul_f32_e32 v57, 0x4b800000, v56
	v_cmp_gt_f32_e32 vcc, s51, v56
	s_nop 1
	v_cndmask_b32_e32 v56, v56, v57, vcc
	v_rsq_f32_e32 v56, v56
	s_nop 0
	v_mul_f32_e32 v57, 0x45800000, v56
	v_cndmask_b32_e32 v56, v56, v57, vcc
	v_lshlrev_b32_e32 v58, 16, v40
	v_and_b32_e32 v59, 0xffff0000, v40
	v_lshlrev_b32_e32 v60, 16, v41
	v_and_b32_e32 v61, 0xffff0000, v41
	v_lshlrev_b32_e32 v62, 16, v42
	v_and_b32_e32 v63, 0xffff0000, v42
	v_lshlrev_b32_e32 v64, 16, v43
	v_and_b32_e32 v65, 0xffff0000, v43
	v_mul_f32_e32 v66, 0xbfb8aa3b, v58
	v_mul_f32_e32 v67, 0xbfb8aa3b, v59
	v_mul_f32_e32 v68, 0xbfb8aa3b, v60
	v_mul_f32_e32 v69, 0xbfb8aa3b, v61
	v_mul_f32_e32 v70, 0xbfb8aa3b, v62
	v_mul_f32_e32 v71, 0xbfb8aa3b, v63
	v_mul_f32_e32 v72, 0xbfb8aa3b, v64
	v_mul_f32_e32 v73, 0xbfb8aa3b, v65
	v_exp_f32_e32 v66, v66
	v_exp_f32_e32 v67, v67
	v_exp_f32_e32 v68, v68
	v_exp_f32_e32 v69, v69
	v_exp_f32_e32 v70, v70
	v_exp_f32_e32 v71, v71
; DI float shx(float v, int m) { return __int_as_float(__builtin_amdgcn_ds_bpermute((lane_now() ^ m) << 2, __float_as_int(v))); }
; DI int shx(int v, int m) { return __builtin_amdgcn_ds_bpermute((lane_now() ^ m) << 2, v); }
; DI u16 f2bf(float x) { return (u16)(pk2bf(x, 0.f) & 0xffffu); }
; DI float bfs(short v) { return __uint_as_float(((unsigned)(u16)v) << 16); }
; DI void phase_scan_c(int wv_, int vb_, int nvb_, char* ws_, const Ctx& p, char* smem, int half) {
;     ...
;   if ((vb_ >> 1) < 64 && (vb_ & 1)) { for (int q_ = 0; q_ < 66; ++q_) __syncthreads(); }
; DI void phase_outnorm_c(int wv_, int vb_, int nvb_, char* ws_, const Ctx& p) {
;     ...
;     for (int q = 0; q < 4; ++q) {
;       float f[8]; float ss = 0.f;
; #pragma unroll
;       for (int j = 0; j < 8; ++j) { f[j] = bfs(ov[q][j]); ss += f[j] * f[j]; }
;       ss += shx(ss, 1); ss += shx(ss, 2); ss += shx(ss, 4); ss += shx(ss, 8);
;       const float rn = rsqrtf(ss * (1.0f / 128.0f) + 1e-6f);
;       bf16x8 o;
; #pragma unroll
;       for (int j = 0; j < 8; ++j) { float gt = bfs(gv[q][j]); float sl = gt * __builtin_amdgcn_rcpf(1.0f + __expf(-gt)); o[j] = (short)f2bf(f[j] * rn * og[j] * sl); }
;       if (ok[q]) *(bf16x8*)(O + ((idx0 + q * stride) >> 4) * 128 + e * 8) = o;
	v_exp_f32_e32 v72, v72
	v_exp_f32_e32 v73, v73
	v_add_f32_e32 v66, 1.0, v66
	v_add_f32_e32 v67, 1.0, v67
	v_add_f32_e32 v68, 1.0, v68
	v_add_f32_e32 v69, 1.0, v69
	v_add_f32_e32 v70, 1.0, v70
	v_add_f32_e32 v71, 1.0, v71
	v_add_f32_e32 v72, 1.0, v72
	v_add_f32_e32 v73, 1.0, v73
	v_rcp_f32_e32 v66, v66
	v_rcp_f32_e32 v67, v67
	v_rcp_f32_e32 v68, v68
	v_rcp_f32_e32 v69, v69
	v_rcp_f32_e32 v70, v70
	v_rcp_f32_e32 v71, v71
	v_rcp_f32_e32 v72, v72
	v_rcp_f32_e32 v73, v73
	v_mul_f32_e32 v66, v66, v58
	v_mul_f32_e32 v67, v67, v59
	v_mul_f32_e32 v68, v68, v60
	v_mul_f32_e32 v69, v69, v61
	v_mul_f32_e32 v70, v70, v62
	v_mul_f32_e32 v71, v71, v63
	v_mul_f32_e32 v72, v72, v64
	v_mul_f32_e32 v73, v73, v65
	v_mul_f32_e32 v48, v56, v48
	v_mul_f32_e32 v49, v56, v49
	v_mul_f32_e32 v50, v56, v50
	v_mul_f32_e32 v51, v56, v51
	v_mul_f32_e32 v52, v56, v52
	v_mul_f32_e32 v53, v56, v53
	v_mul_f32_e32 v54, v56, v54
	v_mul_f32_e32 v55, v56, v55
	v_mul_f32_e32 v48, v2, v48
	v_mul_f32_e32 v49, v3, v49
	v_mul_f32_e32 v50, v4, v50
	v_mul_f32_e32 v51, v5, v51
	v_mul_f32_e32 v52, v6, v52
	v_mul_f32_e32 v53, v7, v53
	v_mul_f32_e32 v54, v8, v54
	v_mul_f32_e32 v55, v9, v55
	v_mul_f32_e32 v48, v66, v48
	v_mul_f32_e32 v49, v67, v49
	v_mul_f32_e32 v50, v68, v50
	v_mul_f32_e32 v51, v69, v51
	v_mul_f32_e32 v52, v70, v52
	v_mul_f32_e32 v53, v71, v53
	v_mul_f32_e32 v54, v72, v54
	v_mul_f32_e32 v55, v73, v55
	v_cvt_pk_bf16_f32 v24, v48, v49
	v_cvt_pk_bf16_f32 v25, v50, v51
	v_cvt_pk_bf16_f32 v26, v52, v53
	v_cvt_pk_bf16_f32 v27, v54, v55
	s_add_u32 s12, s12, 0x8000
	s_addc_u32 s13, s13, 0
	global_store_dwordx4 v13, v[24:27], s[12:13]
	s_waitcnt vmcnt(3)
	v_lshlrev_b32_e32 v48, 16, v28
	v_and_b32_e32 v49, 0xffff0000, v28
	v_lshlrev_b32_e32 v50, 16, v29
	v_and_b32_e32 v51, 0xffff0000, v29
	v_lshlrev_b32_e32 v52, 16, v30
	v_and_b32_e32 v53, 0xffff0000, v30
	v_lshlrev_b32_e32 v54, 16, v31
	v_and_b32_e32 v55, 0xffff0000, v31
	v_mul_f32_e32 v56, v48, v48
	v_mul_f32_e32 v57, v49, v49
	v_add_f32_e32 v56, v56, v57
	v_mul_f32_e32 v57, v50, v50
	v_add_f32_e32 v56, v57, v56
	v_mul_f32_e32 v57, v51, v51
	v_add_f32_e32 v56, v57, v56
	v_mul_f32_e32 v57, v52, v52
	v_add_f32_e32 v56, v57, v56
	v_mul_f32_e32 v57, v53, v53
	v_add_f32_e32 v56, v57, v56
	v_mul_f32_e32 v57, v54, v54
	v_add_f32_e32 v56, v57, v56
	v_mul_f32_e32 v57, v55, v55
	v_add_f32_e32 v56, v57, v56
	s_nop 1
	v_add_f32_dpp v56, v56, v56 quad_perm:[1,0,3,2] row_mask:0xf bank_mask:0xf
	s_nop 1
	v_add_f32_dpp v56, v56, v56 quad_perm:[2,3,0,1] row_mask:0xf bank_mask:0xf
	s_nop 1
	v_add_f32_dpp v56, v56, v56 row_half_mirror row_mask:0xf bank_mask:0xf
	s_nop 1
	v_add_f32_dpp v56, v56, v56 row_mirror row_mask:0xf bank_mask:0xf
	v_fmamk_f32 v56, v56, 0x3c000000, v206
	v_mul_f32_e32 v57, 0x4b800000, v56
	v_cmp_gt_f32_e32 vcc, s51, v56
	s_nop 1
	v_cndmask_b32_e32 v56, v56, v57, vcc
	v_rsq_f32_e32 v56, v56
	s_nop 0
	v_mul_f32_e32 v57, 0x45800000, v56
	v_cndmask_b32_e32 v56, v56, v57, vcc
	v_lshlrev_b32_e32 v58, 16, v44
	v_and_b32_e32 v59, 0xffff0000, v44
	v_lshlrev_b32_e32 v60, 16, v45
	v_and_b32_e32 v61, 0xffff0000, v45
	v_lshlrev_b32_e32 v62, 16, v46
	v_and_b32_e32 v63, 0xffff0000, v46
	v_lshlrev_b32_e32 v64, 16, v47
	v_and_b32_e32 v65, 0xffff0000, v47
	v_mul_f32_e32 v66, 0xbfb8aa3b, v58
	v_mul_f32_e32 v67, 0xbfb8aa3b, v59
	v_mul_f32_e32 v68, 0xbfb8aa3b, v60
	v_mul_f32_e32 v69, 0xbfb8aa3b, v61
	v_mul_f32_e32 v70, 0xbfb8aa3b, v62
	v_mul_f32_e32 v71, 0xbfb8aa3b, v63
	v_mul_f32_e32 v72, 0xbfb8aa3b, v64
	v_mul_f32_e32 v73, 0xbfb8aa3b, v65
	v_exp_f32_e32 v66, v66
	v_exp_f32_e32 v67, v67
	v_exp_f32_e32 v68, v68
	v_exp_f32_e32 v69, v69
	v_exp_f32_e32 v70, v70
	v_exp_f32_e32 v71, v71
	v_exp_f32_e32 v72, v72
	v_exp_f32_e32 v73, v73
	v_add_f32_e32 v66, 1.0, v66
	v_add_f32_e32 v67, 1.0, v67
	v_add_f32_e32 v68, 1.0, v68
	v_add_f32_e32 v69, 1.0, v69
	v_add_f32_e32 v70, 1.0, v70
	v_add_f32_e32 v71, 1.0, v71
	v_add_f32_e32 v72, 1.0, v72
	v_add_f32_e32 v73, 1.0, v73
	v_rcp_f32_e32 v66, v66
	v_rcp_f32_e32 v67, v67
	v_rcp_f32_e32 v68, v68
	v_rcp_f32_e32 v69, v69
	v_rcp_f32_e32 v70, v70
	v_rcp_f32_e32 v71, v71
	v_rcp_f32_e32 v72, v72
	v_rcp_f32_e32 v73, v73
	v_mul_f32_e32 v66, v66, v58
	v_mul_f32_e32 v67, v67, v59
	v_mul_f32_e32 v68, v68, v60
	v_mul_f32_e32 v69, v69, v61
	v_mul_f32_e32 v70, v70, v62
	v_mul_f32_e32 v71, v71, v63
	v_mul_f32_e32 v72, v72, v64
	v_mul_f32_e32 v73, v73, v65
	v_mul_f32_e32 v48, v56, v48
	v_mul_f32_e32 v49, v56, v49
	v_mul_f32_e32 v50, v56, v50
	v_mul_f32_e32 v51, v56, v51
	v_mul_f32_e32 v52, v56, v52
	v_mul_f32_e32 v53, v56, v53
	v_mul_f32_e32 v54, v56, v54
	v_mul_f32_e32 v55, v56, v55
	v_mul_f32_e32 v48, v2, v48
	v_mul_f32_e32 v49, v3, v49
	v_mul_f32_e32 v50, v4, v50
	v_mul_f32_e32 v51, v5, v51
	v_mul_f32_e32 v52, v6, v52
	v_mul_f32_e32 v53, v7, v53
	v_mul_f32_e32 v54, v8, v54
	v_mul_f32_e32 v55, v9, v55
	v_mul_f32_e32 v48, v66, v48
	v_mul_f32_e32 v49, v67, v49
	v_mul_f32_e32 v50, v68, v50
	v_mul_f32_e32 v51, v69, v51
	v_mul_f32_e32 v52, v70, v52
	v_mul_f32_e32 v53, v71, v53
	v_mul_f32_e32 v54, v72, v54
	v_mul_f32_e32 v55, v73, v55
	v_cvt_pk_bf16_f32 v28, v48, v49
	v_cvt_pk_bf16_f32 v29, v50, v51
	v_cvt_pk_bf16_f32 v30, v52, v53
	v_cvt_pk_bf16_f32 v31, v54, v55
	s_add_u32 s12, s12, 0x8000
	s_addc_u32 s13, s13, 0
	global_store_dwordx4 v13, v[28:31], s[12:13]
	s_add_u32 s4, s4, 0x20000
	s_addc_u32 s5, s5, 0
	s_add_u32 s6, s6, 0x20000
	s_addc_u32 s7, s7, 0
.Long_noproc:
	s_cmp_eq_u32 s10, 32
	s_cbranch_scc1 .Long_done
	s_barrier
	s_add_i32 s10, s10, 1
	s_branch .Long_loop
.Long_done:
	s_nop 0
	s_nop 0
	s_nop 0
	s_nop 0
	s_nop 0
	s_nop 0
	s_nop 0
	s_nop 0
	s_nop 0
	s_nop 0
	s_nop 0
	s_nop 0
	s_nop 0
	s_nop 0
	s_waitcnt vmcnt(0)
	s_mov_b32 s0, s33
	v_mov_b32_e32 v2, v204

; #define MFMA32(a, b, c) __builtin_amdgcn_mfma_f32_32x32x16_bf16((a), (b), (c), 0, 0, 0)
; DI void phase_scan_c(int wv_, int vb_, int nvb_, char* ws_, const Ctx& p, char* smem, int half) {
;     ...
;       const size_t uix = (size_t)blk * 32 + nc;
;       const float egl = GL[uix];
;       bf16x8 ucur[4];
; #pragma unroll
;       for (int tb = 0; tb < 2; ++tb) { ucur[2 * tb] = *(const bf16x8*)(CU + (uix * 128 + dv0 + c) * 64 + h * 16 + tb * 32); ucur[2 * tb + 1] = *(const bf16x8*)(CU + (uix * 128 + dv0 + c) * 64 + h * 16 + tb * 32 + 8); }
;       const u16* Wp = sW + c * 136 + h * 8;
;       const u16* Qp = sQ + c * 136 + h * 8;
;       const u16* KTp = sKT + c * 72 + h * 8;
;       const u16* QKp = sQK + c * 72 + h * 8;
;       f32x16 X[2], Oa[2];
;       X[0] = zero16(); X[1] = zero16(); Oa[0] = zero16(); Oa[1] = zero16();
; #pragma unroll
;       for (int mb = 0; mb < 4; ++mb) {
; #pragma unroll
;         for (int s = 0; s < 2; ++s) {
;           const bf16x8 sb = pack8(S[mb], s);
; #pragma unroll
;           for (int tb = 0; tb < 2; ++tb) {
;             bf16x8 a = *(const bf16x8*)(Wp + tb * 32 * 136 + mb * 32 + s * 16);
;             bf16x8 a2 = *(const bf16x8*)(Qp + tb * 32 * 136 + mb * 32 + s * 16);
;             X[tb] = MFMA32(a, sb, X[tb]);
;             Oa[tb] = MFMA32(a2, sb, Oa[tb]);
;           }
;         }
;       }
.LBB0_167:
	s_add_u32 s12, s2, s16
	s_addc_u32 s13, s3, s17
	v_lshl_add_u64 v[66:67], v[188:189], 0, s[16:17]
	global_load_dword v0, v1, s[12:13]
	global_load_dwordx4 v[142:145], v[66:67], off offset:-64
	global_load_dwordx4 v[138:141], v[66:67], off offset:-48
	global_load_dwordx4 v[134:137], v[66:67], off
	global_load_dwordx4 v[130:133], v[66:67], off offset:16
	ds_read_b128 v[70:73], v179 offset:17408
	ds_read_b128 v[74:77], v179
	ds_read_b128 v[146:149], v179 offset:32
	v_cvt_pk_bf16_f32 v66, v18, v19
	v_cvt_pk_bf16_f32 v67, v20, v21
	v_cvt_pk_bf16_f32 v68, v22, v23
	v_cvt_pk_bf16_f32 v69, v24, v25
	v_cvt_pk_bf16_f32 v150, v26, v27
	v_cvt_pk_bf16_f32 v151, v28, v29
	s_waitcnt lgkmcnt(1)
	v_mfma_f32_32x32x16_bf16 v[114:129], v[74:77], v[66:69], 0
	v_cvt_pk_bf16_f32 v152, v30, v31
	v_cvt_pk_bf16_f32 v153, v32, v33
	v_add_co_u32_e64 v183, s[12:13], s1, 1
	s_add_i32 s1, s1, 33
	s_and_b64 s[12:13], s[12:13], exec
	s_cselect_b32 s1, 31, s1
	v_mfma_f32_32x32x16_bf16 v[82:97], v[70:73], v[66:69], 0
	ds_read_b128 v[70:73], v179 offset:8704
	ds_read_b128 v[74:77], v179 offset:26112
	ds_read_b128 v[154:157], v179 offset:17440
	s_add_u32 s12, s44, s1
	s_addc_u32 s13, s45, 0
	s_lshl_b64 s[14:15], s[12:13], 13
	s_lshl_b64 s[12:13], s[12:13], 14
	s_add_u32 s18, s4, s12
	s_waitcnt lgkmcnt(2)
	v_mfma_f32_32x32x16_bf16 v[98:113], v[70:73], v[66:69], 0
	s_addc_u32 s19, s5, s13
	s_add_u32 s34, s6, s12
	s_addc_u32 s35, s7, s13
	s_add_u32 s12, s8, s12
	s_addc_u32 s13, s9, s13
	v_lshl_add_u64 v[158:159], s[12:13], 0, v[202:203]
	v_readfirstlane_b32 s0, v183
	s_waitcnt lgkmcnt(1)
	v_mfma_f32_32x32x16_bf16 v[66:81], v[74:77], v[66:69], 0
	v_lshl_add_u64 v[188:189], v[188:189], 0, s[94:95]
	s_mov_b32 s1, s0
	s_waitcnt vmcnt(4)
	v_mul_f32_e64 v32, v32, v0
	v_mul_f32_e64 v33, v33, v0
	v_mfma_f32_32x32x16_bf16 v[114:129], v[146:149], v[150:153], v[114:129]
	v_mul_f32_e64 v30, v30, v0
	v_mul_f32_e64 v31, v31, v0
	v_mul_f32_e64 v28, v28, v0
	v_mul_f32_e64 v29, v29, v0
	v_mul_f32_e64 v26, v26, v0
	v_mul_f32_e64 v27, v27, v0
	v_pk_mul_f32 v[24:25], v[24:25], v[0:1] op_sel_hi:[1,0]
	v_pk_mul_f32 v[22:23], v[22:23], v[0:1] op_sel_hi:[1,0]
	v_pk_mul_f32 v[20:21], v[20:21], v[0:1] op_sel_hi:[1,0]
	v_pk_mul_f32 v[18:19], v[18:19], v[0:1] op_sel_hi:[1,0]
	s_waitcnt lgkmcnt(0)
	v_mfma_f32_32x32x16_bf16 v[82:97], v[154:157], v[150:153], v[82:97]
	ds_read_b128 v[146:149], v179 offset:8736
	ds_read_b128 v[154:157], v179 offset:26144
	s_waitcnt lgkmcnt(1)
	v_mfma_f32_32x32x16_bf16 v[98:113], v[146:149], v[150:153], v[98:113]
	v_cvt_pk_bf16_f32 v146, v50, v51
	v_cvt_pk_bf16_f32 v147, v52, v53
	v_cvt_pk_bf16_f32 v148, v54, v55
	v_cvt_pk_bf16_f32 v149, v56, v57
	v_mul_f32_e64 v56, v56, v0
	v_mul_f32_e64 v57, v57, v0
	v_pk_mul_f32 v[54:55], v[54:55], v[0:1] op_sel_hi:[1,0]
	v_pk_mul_f32 v[52:53], v[52:53], v[0:1] op_sel_hi:[1,0]
	s_waitcnt lgkmcnt(0)
	v_mfma_f32_32x32x16_bf16 v[66:81], v[154:157], v[150:153], v[66:81]
	ds_read_b128 v[150:153], v179 offset:64
	ds_read_b128 v[154:157], v179 offset:17472
	v_mul_f32_e64 v50, v50, v0
	v_mul_f32_e64 v51, v51, v0
	s_waitcnt lgkmcnt(1)
	v_mfma_f32_32x32x16_bf16 v[114:129], v[150:153], v[146:149], v[114:129]
	s_waitcnt lgkmcnt(0)
	v_mfma_f32_32x32x16_bf16 v[82:97], v[154:157], v[146:149], v[82:97]
	ds_read_b128 v[150:153], v179 offset:8768
	ds_read_b128 v[154:157], v179 offset:26176
	s_waitcnt lgkmcnt(1)
	v_mfma_f32_32x32x16_bf16 v[98:113], v[150:153], v[146:149], v[98:113]
	s_waitcnt lgkmcnt(0)
	v_mfma_f32_32x32x16_bf16 v[66:81], v[154:157], v[146:149], v[66:81]
	ds_read_b128 v[150:153], v179 offset:96
	ds_read_b128 v[154:157], v179 offset:17504
	v_cvt_pk_bf16_f32 v146, v58, v59
	v_cvt_pk_bf16_f32 v147, v60, v61
	v_cvt_pk_bf16_f32 v148, v62, v63
	v_cvt_pk_bf16_f32 v149, v64, v65
	v_pk_mul_f32 v[64:65], v[64:65], v[0:1] op_sel_hi:[1,0]
	v_pk_mul_f32 v[62:63], v[62:63], v[0:1] op_sel_hi:[1,0]
	s_waitcnt lgkmcnt(1)
	v_mfma_f32_32x32x16_bf16 v[114:129], v[150:153], v[146:149], v[114:129]
	v_mul_f32_e64 v60, v60, v0
	v_mul_f32_e64 v61, v61, v0
	v_mul_f32_e64 v58, v58, v0
	v_mul_f32_e64 v59, v59, v0
	s_waitcnt lgkmcnt(0)
	v_mfma_f32_32x32x16_bf16 v[82:97], v[154:157], v[146:149], v[82:97]
	ds_read_b128 v[150:153], v179 offset:8800
	ds_read_b128 v[154:157], v179 offset:26208
	s_waitcnt lgkmcnt(1)
	v_mfma_f32_32x32x16_bf16 v[98:113], v[150:153], v[146:149], v[98:113]
	s_waitcnt lgkmcnt(0)
	v_mfma_f32_32x32x16_bf16 v[66:81], v[154:157], v[146:149], v[66:81]
	ds_read_b128 v[150:153], v179 offset:128
	ds_read_b128 v[154:157], v179 offset:17536
	v_cvt_pk_bf16_f32 v146, v34, v35
	v_cvt_pk_bf16_f32 v147, v36, v37
	v_cvt_pk_bf16_f32 v148, v38, v39
	v_cvt_pk_bf16_f32 v149, v40, v41
	v_pk_mul_f32 v[40:41], v[40:41], v[0:1] op_sel_hi:[1,0]
	v_pk_mul_f32 v[38:39], v[38:39], v[0:1] op_sel_hi:[1,0]
	s_waitcnt lgkmcnt(1)
	v_mfma_f32_32x32x16_bf16 v[114:129], v[150:153], v[146:149], v[114:129]
	v_mul_f32_e64 v36, v36, v0
	v_mul_f32_e64 v37, v37, v0
	v_mul_f32_e64 v34, v34, v0
	v_mul_f32_e64 v35, v35, v0
	s_waitcnt lgkmcnt(0)
	v_mfma_f32_32x32x16_bf16 v[82:97], v[154:157], v[146:149], v[82:97]
	ds_read_b128 v[150:153], v179 offset:8832
	ds_read_b128 v[154:157], v179 offset:26240
	s_waitcnt lgkmcnt(1)
	v_mfma_f32_32x32x16_bf16 v[98:113], v[150:153], v[146:149], v[98:113]
	s_waitcnt lgkmcnt(0)
	v_mfma_f32_32x32x16_bf16 v[66:81], v[154:157], v[146:149], v[66:81]
	ds_read_b128 v[150:153], v179 offset:160
	ds_read_b128 v[154:157], v179 offset:17568
	v_cvt_pk_bf16_f32 v146, v42, v43
	v_cvt_pk_bf16_f32 v147, v44, v45
	v_cvt_pk_bf16_f32 v148, v46, v47
	v_cvt_pk_bf16_f32 v149, v48, v49
	v_pk_mul_f32 v[48:49], v[48:49], v[0:1] op_sel_hi:[1,0]
	v_pk_mul_f32 v[46:47], v[46:47], v[0:1] op_sel_hi:[1,0]
	s_waitcnt lgkmcnt(1)
; #define MFMA32(a, b, c) __builtin_amdgcn_mfma_f32_32x32x16_bf16((a), (b), (c), 0, 0, 0)
; DI float bfs(short v) { return __uint_as_float(((unsigned)(u16)v) << 16); }
; DI void phase_scan_c(int wv_, int vb_, int nvb_, char* ws_, const Ctx& p, char* smem, int half) {
;     ...
; #pragma unroll
;       for (int mb = 0; mb < 4; ++mb) {
; #pragma unroll
;         for (int s = 0; s < 2; ++s) {
;           const bf16x8 sb = pack8(S[mb], s);
; #pragma unroll
;           for (int tb = 0; tb < 2; ++tb) {
;             bf16x8 a = *(const bf16x8*)(Wp + tb * 32 * 136 + mb * 32 + s * 16);
;             bf16x8 a2 = *(const bf16x8*)(Qp + tb * 32 * 136 + mb * 32 + s * 16);
;             X[tb] = MFMA32(a, sb, X[tb]);
;             Oa[tb] = MFMA32(a2, sb, Oa[tb]);
;           }
;         }
;       }
;       bf16x8 vb[2][2];
; #pragma unroll
;       for (int tb = 0; tb < 2; ++tb) {
; #pragma unroll
;         for (int i = 0; i < 8; ++i) { X[tb][i] = bfs(ucur[2 * tb][i]) - X[tb][i]; X[tb][8 + i] = bfs(ucur[2 * tb + 1][i]) - X[tb][8 + i]; }
;         vb[tb][0] = pack8(X[tb], 0); vb[tb][1] = pack8(X[tb], 1);
;       }
;       { const int ncn = nc < 31 ? nc + 1 : 31; SLOAD((size_t)blk * 32 + ncn) }
; #pragma unroll
;       for (int tb = 0; tb < 2; ++tb)
; #pragma unroll
;         for (int tb2 = 0; tb2 < 2; ++tb2)
; #pragma unroll
;           for (int s = 0; s < 2; ++s) {
;             bf16x8 a = *(const bf16x8*)(QKp + tb * 32 * 72 + tb2 * 32 + s * 16);
;             Oa[tb] = MFMA32(a, vb[tb2][s], Oa[tb]);
;           }
	v_mfma_f32_32x32x16_bf16 v[114:129], v[150:153], v[146:149], v[114:129]
	v_mul_f32_e64 v44, v44, v0
	v_mul_f32_e64 v45, v45, v0
	v_mul_f32_e64 v42, v42, v0
	v_mul_f32_e64 v43, v43, v0
	s_waitcnt lgkmcnt(0)
	v_mfma_f32_32x32x16_bf16 v[82:97], v[154:157], v[146:149], v[82:97]
	ds_read_b128 v[150:153], v179 offset:8864
	ds_read_b128 v[154:157], v179 offset:26272
	s_waitcnt lgkmcnt(1)
	v_mfma_f32_32x32x16_bf16 v[98:113], v[150:153], v[146:149], v[98:113]
	s_waitcnt lgkmcnt(0)
	v_mfma_f32_32x32x16_bf16 v[66:81], v[154:157], v[146:149], v[66:81]
	ds_read_b128 v[150:153], v179 offset:192
	ds_read_b128 v[154:157], v179 offset:17600
	v_cvt_pk_bf16_f32 v146, v2, v3
	v_cvt_pk_bf16_f32 v147, v4, v5
	v_cvt_pk_bf16_f32 v148, v6, v7
	v_cvt_pk_bf16_f32 v149, v8, v9
	v_pk_mul_f32 v[8:9], v[8:9], v[0:1] op_sel_hi:[1,0]
	v_pk_mul_f32 v[6:7], v[6:7], v[0:1] op_sel_hi:[1,0]
	s_waitcnt lgkmcnt(1)
	v_mfma_f32_32x32x16_bf16 v[114:129], v[150:153], v[146:149], v[114:129]
	v_mul_f32_e64 v4, v4, v0
	v_mul_f32_e64 v5, v5, v0
	v_mul_f32_e64 v2, v2, v0
	v_mul_f32_e64 v3, v3, v0
	s_waitcnt lgkmcnt(0)
	v_mfma_f32_32x32x16_bf16 v[82:97], v[154:157], v[146:149], v[82:97]
	ds_read_b128 v[150:153], v179 offset:8896
	ds_read_b128 v[154:157], v179 offset:26304
	s_waitcnt lgkmcnt(1)
	v_mfma_f32_32x32x16_bf16 v[98:113], v[150:153], v[146:149], v[98:113]
	s_waitcnt lgkmcnt(0)
	v_mfma_f32_32x32x16_bf16 v[66:81], v[154:157], v[146:149], v[66:81]
	ds_read_b128 v[150:153], v179 offset:224
	ds_read_b128 v[154:157], v179 offset:17632
	v_cvt_pk_bf16_f32 v146, v10, v11
	v_cvt_pk_bf16_f32 v147, v12, v13
	v_cvt_pk_bf16_f32 v148, v14, v15
	v_cvt_pk_bf16_f32 v149, v16, v17
	v_pk_mul_f32 v[16:17], v[16:17], v[0:1] op_sel_hi:[1,0]
	v_pk_mul_f32 v[14:15], v[14:15], v[0:1] op_sel_hi:[1,0]
	s_waitcnt lgkmcnt(1)
	v_mfma_f32_32x32x16_bf16 v[114:129], v[150:153], v[146:149], v[114:129]
	v_mul_f32_e64 v12, v12, v0
	v_mul_f32_e64 v13, v13, v0
	v_mul_f32_e64 v10, v10, v0
	v_mul_f32_e64 v11, v11, v0
	s_waitcnt lgkmcnt(0)
	v_mfma_f32_32x32x16_bf16 v[82:97], v[154:157], v[146:149], v[82:97]
	ds_read_b128 v[150:153], v179 offset:8928
	ds_read_b128 v[154:157], v179 offset:26336
	ds_read_b128 v[218:221], v181 offset:53248
	global_load_dwordx4 v[158:161], v[158:159], off
	s_waitcnt lgkmcnt(2)
	v_mfma_f32_32x32x16_bf16 v[98:113], v[150:153], v[146:149], v[98:113]
	v_lshl_add_u64 v[150:151], s[18:19], 0, v[202:203]
	global_load_dwordx4 v[150:153], v[150:151], off
	s_waitcnt lgkmcnt(1)
	v_mfma_f32_32x32x16_bf16 v[66:81], v[154:157], v[146:149], v[66:81]
	s_waitcnt vmcnt(5)
	v_and_b32_e32 v147, 0xffff0000, v142
	v_lshlrev_b32_e32 v146, 16, v142
	v_add_f32_e64 v114, v146, -v114
	v_add_f32_e64 v115, v147, -v115
	s_waitcnt vmcnt(4)
	v_and_b32_e32 v147, 0xffff0000, v138
	v_lshlrev_b32_e32 v146, 16, v138
	v_pk_add_f32 v[122:123], v[146:147], v[122:123] neg_lo:[0,1] neg_hi:[0,1]
	v_and_b32_e32 v147, 0xffff0000, v143
	v_lshlrev_b32_e32 v146, 16, v143
	v_and_b32_e32 v143, 0xffff0000, v139
	v_lshlrev_b32_e32 v142, 16, v139
	v_and_b32_e32 v139, 0xffff0000, v144
	v_lshlrev_b32_e32 v138, 16, v144
	v_pk_add_f32 v[138:139], v[138:139], v[118:119] neg_lo:[0,1] neg_hi:[0,1]
	v_and_b32_e32 v119, 0xffff0000, v140
	v_lshlrev_b32_e32 v118, 16, v140
	v_pk_add_f32 v[126:127], v[118:119], v[126:127] neg_lo:[0,1] neg_hi:[0,1]
	v_and_b32_e32 v119, 0xffff0000, v145
	v_lshlrev_b32_e32 v118, 16, v145
	v_pk_add_f32 v[116:117], v[146:147], v[116:117] neg_lo:[0,1] neg_hi:[0,1]
	v_pk_add_f32 v[124:125], v[142:143], v[124:125] neg_lo:[0,1] neg_hi:[0,1]
	v_pk_add_f32 v[142:143], v[118:119], v[120:121] neg_lo:[0,1] neg_hi:[0,1]
	v_and_b32_e32 v119, 0xffff0000, v141
	v_lshlrev_b32_e32 v118, 16, v141
	v_pk_add_f32 v[128:129], v[118:119], v[128:129] neg_lo:[0,1] neg_hi:[0,1]
	v_cvt_pk_bf16_f32 v118, v114, v115
	v_cvt_pk_bf16_f32 v119, v116, v117
	v_cvt_pk_bf16_f32 v120, v138, v139
	v_cvt_pk_bf16_f32 v121, v142, v143
	v_cvt_pk_bf16_f32 v114, v122, v123
	v_cvt_pk_bf16_f32 v115, v124, v125
	s_waitcnt lgkmcnt(0)
	v_mfma_f32_32x32x16_bf16 v[82:97], v[218:221], v[118:121], v[82:97]
	ds_read_b128 v[218:221], v181 offset:53280
	v_cvt_pk_bf16_f32 v116, v126, v127
	v_cvt_pk_bf16_f32 v117, v128, v129
	s_waitcnt vmcnt(3)
	v_and_b32_e32 v123, 0xffff0000, v134
	v_lshlrev_b32_e32 v122, 16, v134
	v_pk_add_f32 v[98:99], v[122:123], v[98:99] neg_lo:[0,1] neg_hi:[0,1]
	s_waitcnt vmcnt(2)
	v_and_b32_e32 v123, 0xffff0000, v130
	s_waitcnt lgkmcnt(0)
	v_mfma_f32_32x32x16_bf16 v[82:97], v[218:221], v[114:117], v[82:97]
	ds_read_b128 v[218:221], v181 offset:53312
	v_lshlrev_b32_e32 v122, 16, v130
	v_add_f32_e64 v106, v122, -v106
	v_add_f32_e64 v107, v123, -v107
	v_and_b32_e32 v123, 0xffff0000, v135
	v_lshlrev_b32_e32 v122, 16, v135
	v_pk_add_f32 v[100:101], v[122:123], v[100:101] neg_lo:[0,1] neg_hi:[0,1]
	v_and_b32_e32 v123, 0xffff0000, v131
	v_lshlrev_b32_e32 v122, 16, v131
	v_pk_add_f32 v[108:109], v[122:123], v[108:109] neg_lo:[0,1] neg_hi:[0,1]
	v_and_b32_e32 v123, 0xffff0000, v136
	v_lshlrev_b32_e32 v122, 16, v136
	v_pk_add_f32 v[122:123], v[122:123], v[102:103] neg_lo:[0,1] neg_hi:[0,1]
	v_and_b32_e32 v103, 0xffff0000, v132
	v_lshlrev_b32_e32 v102, 16, v132
	v_pk_add_f32 v[110:111], v[102:103], v[110:111] neg_lo:[0,1] neg_hi:[0,1]
	v_and_b32_e32 v103, 0xffff0000, v137
	v_lshlrev_b32_e32 v102, 16, v137
	v_pk_add_f32 v[124:125], v[102:103], v[104:105] neg_lo:[0,1] neg_hi:[0,1]
	v_and_b32_e32 v103, 0xffff0000, v133
	v_lshlrev_b32_e32 v102, 16, v133
	v_pk_add_f32 v[112:113], v[102:103], v[112:113] neg_lo:[0,1] neg_hi:[0,1]
	v_cvt_pk_bf16_f32 v102, v98, v99
	v_cvt_pk_bf16_f32 v103, v100, v101
	v_cvt_pk_bf16_f32 v104, v122, v123
	v_cvt_pk_bf16_f32 v105, v124, v125
	v_cvt_pk_bf16_f32 v98, v106, v107
	v_cvt_pk_bf16_f32 v99, v108, v109
	s_waitcnt lgkmcnt(0)
; #define MFMA32(a, b, c) __builtin_amdgcn_mfma_f32_32x32x16_bf16((a), (b), (c), 0, 0, 0)
; DI void phase_scan_c(int wv_, int vb_, int nvb_, char* ws_, const Ctx& p, char* smem, int half) {
;     ...
;       { const int ncn = nc < 31 ? nc + 1 : 31; SLOAD((size_t)blk * 32 + ncn) }
; #pragma unroll
;       for (int tb = 0; tb < 2; ++tb)
; #pragma unroll
;         for (int tb2 = 0; tb2 < 2; ++tb2)
; #pragma unroll
;           for (int s = 0; s < 2; ++s) {
;             bf16x8 a = *(const bf16x8*)(QKp + tb * 32 * 72 + tb2 * 32 + s * 16);
;             Oa[tb] = MFMA32(a, vb[tb2][s], Oa[tb]);
;           }
; #pragma unroll
;       for (int mb = 0; mb < 4; ++mb) {
; #pragma unroll
;         for (int i = 0; i < 16; ++i) S[mb][i] *= egl;
; #pragma unroll
;         for (int tb = 0; tb < 2; ++tb)
; #pragma unroll
;           for (int s = 0; s < 2; ++s) {
;             bf16x8 a = *(const bf16x8*)(KTp + mb * 32 * 72 + tb * 32 + s * 16);
;             S[mb] = MFMA32(a, vb[tb][s], S[mb]);
;           }
;       }
	v_mfma_f32_32x32x16_bf16 v[82:97], v[218:221], v[102:105], v[82:97]
	ds_read_b128 v[218:221], v181 offset:53344
	v_cvt_pk_bf16_f32 v100, v110, v111
	v_cvt_pk_bf16_f32 v101, v112, v113
	v_lshl_add_u64 v[122:123], s[12:13], 0, v[190:191]
	v_lshl_add_u64 v[134:135], s[12:13], 0, v[192:193]
	v_lshl_add_u64 v[146:147], s[12:13], 0, v[200:201]
	s_add_u32 s12, s10, s14
	s_waitcnt lgkmcnt(0)
	v_mfma_f32_32x32x16_bf16 v[82:97], v[218:221], v[98:101], v[82:97]
	ds_read_b128 v[218:221], v181 offset:57856
	s_addc_u32 s13, s11, s15
	v_lshl_add_u64 v[106:107], s[18:19], 0, v[190:191]
	v_lshl_add_u64 v[110:111], s[34:35], 0, v[190:191]
	v_lshl_add_u64 v[126:127], s[18:19], 0, v[192:193]
	v_lshl_add_u64 v[130:131], s[34:35], 0, v[192:193]
	v_lshl_add_u64 v[138:139], s[18:19], 0, v[200:201]
	s_waitcnt lgkmcnt(0)
	v_mfma_f32_32x32x16_bf16 v[66:81], v[218:221], v[118:121], v[66:81]
	ds_read_b128 v[218:221], v181 offset:57888
	v_lshl_add_u64 v[142:143], s[34:35], 0, v[200:201]
	v_lshl_add_u64 v[154:155], s[34:35], 0, v[202:203]
	v_lshl_add_u64 v[162:163], s[12:13], 0, v[170:171]
	v_lshl_add_u64 v[166:167], s[12:13], 0, v[172:173]
	global_load_dwordx4 v[106:109], v[106:107], off
	v_cvt_pk_bf16_f32 v0, v82, s0
	s_waitcnt lgkmcnt(0)
	v_mfma_f32_32x32x16_bf16 v[66:81], v[218:221], v[114:117], v[66:81]
	ds_read_b128 v[218:221], v181 offset:57920
	global_load_dwordx4 v[110:113], v[110:111], off
	s_add_u32 s2, s2, 4
	global_load_dwordx4 v[122:125], v[122:123], off
	s_addc_u32 s3, s3, 0
	global_load_dwordx4 v[126:129], v[126:127], off
	s_waitcnt lgkmcnt(0)
	v_mfma_f32_32x32x16_bf16 v[66:81], v[218:221], v[102:105], v[66:81]
	ds_read_b128 v[218:221], v181 offset:57952
	global_load_dwordx4 v[130:133], v[130:131], off
	s_nop 0
	global_load_dwordx4 v[134:137], v[134:135], off
	s_nop 0
	global_load_dwordx4 v[138:141], v[138:139], off
	s_nop 0
	global_load_dwordx4 v[142:145], v[142:143], off
	s_waitcnt lgkmcnt(0)
	v_mfma_f32_32x32x16_bf16 v[66:81], v[218:221], v[98:101], v[66:81]
	global_load_dwordx4 v[146:149], v[146:147], off
	s_nop 0
	global_load_dwordx4 v[154:157], v[154:155], off
	s_nop 0
	global_load_dwordx4 v[162:165], v[162:163], off
	s_nop 0
	global_load_dwordx4 v[166:169], v[166:167], off
	ds_read_b128 v[218:221], v181 offset:34816
	ds_read_b128 v[222:225], v181 offset:34848
	s_waitcnt lgkmcnt(1)
	v_mfma_f32_32x32x16_bf16 v[18:33], v[218:221], v[118:121], v[18:33]
	ds_read_b128 v[218:221], v181 offset:34880
	s_waitcnt lgkmcnt(1)
	v_mfma_f32_32x32x16_bf16 v[18:33], v[222:225], v[114:117], v[18:33]
	s_waitcnt lgkmcnt(0)
	v_mfma_f32_32x32x16_bf16 v[18:33], v[218:221], v[102:105], v[18:33]
	ds_read_b128 v[218:221], v181 offset:34912
	s_waitcnt lgkmcnt(0)
	v_mfma_f32_32x32x16_bf16 v[18:33], v[218:221], v[98:101], v[18:33]
	ds_read_b128 v[218:221], v181 offset:39424
	s_waitcnt lgkmcnt(0)
	v_mfma_f32_32x32x16_bf16 v[50:65], v[218:221], v[118:121], v[50:65]
	ds_read_b128 v[218:221], v181 offset:39456
	s_waitcnt lgkmcnt(0)
	v_mfma_f32_32x32x16_bf16 v[50:65], v[218:221], v[114:117], v[50:65]
	ds_read_b128 v[218:221], v181 offset:39488
	s_waitcnt lgkmcnt(0)
	v_mfma_f32_32x32x16_bf16 v[50:65], v[218:221], v[102:105], v[50:65]
	ds_read_b128 v[218:221], v181 offset:39520
	s_waitcnt lgkmcnt(0)
	v_mfma_f32_32x32x16_bf16 v[50:65], v[218:221], v[98:101], v[50:65]
	ds_read_b128 v[218:221], v181 offset:44032
	s_waitcnt lgkmcnt(0)
	v_mfma_f32_32x32x16_bf16 v[34:49], v[218:221], v[118:121], v[34:49]
	ds_read_b128 v[218:221], v181 offset:44064
	s_waitcnt lgkmcnt(0)
	v_mfma_f32_32x32x16_bf16 v[34:49], v[218:221], v[114:117], v[34:49]
	ds_read_b128 v[218:221], v181 offset:44096
	s_waitcnt lgkmcnt(0)
	v_mfma_f32_32x32x16_bf16 v[34:49], v[218:221], v[102:105], v[34:49]
	ds_read_b128 v[218:221], v181 offset:44128
	s_waitcnt lgkmcnt(0)
	v_mfma_f32_32x32x16_bf16 v[34:49], v[218:221], v[98:101], v[34:49]
	ds_read_b128 v[218:221], v181 offset:48640
	s_waitcnt lgkmcnt(0)
	v_mfma_f32_32x32x16_bf16 v[2:17], v[218:221], v[118:121], v[2:17]
	ds_read_b128 v[118:121], v181 offset:48672
	s_waitcnt lgkmcnt(0)
	v_mfma_f32_32x32x16_bf16 v[2:17], v[118:121], v[114:117], v[2:17]
	ds_read_b128 v[114:117], v181 offset:48704
	s_waitcnt lgkmcnt(0)
	v_mfma_f32_32x32x16_bf16 v[2:17], v[114:117], v[102:105], v[2:17]
	ds_read_b128 v[102:105], v181 offset:48736
	s_waitcnt lgkmcnt(0)
; DI u16 f2bf(float x) { return (u16)(pk2bf(x, 0.f) & 0xffffu); }
; DI int crow(int i, int h) { return (i & 3) + 8 * (i >> 2) + 4 * h; }
; DI void phase_scan_c(int wv_, int vb_, int nvb_, char* ws_, const Ctx& p, char* smem, int half) {
;     ...
;       u16* op = O + ((size_t)b * SEQ + (size_t)(half * 32 + nc) * 64) * 1024 + hd * 128 + dv0 + c;
; #pragma unroll
;       for (int tb = 0; tb < 2; ++tb)
; #pragma unroll
;         for (int i = 0; i < 16; ++i) op[(size_t)(tb * 32 + crow(i, h)) * 1024] = f2bf(Oa[tb][i]);
;       __syncthreads();
;       SWRITE()
;       __syncthreads();
	v_mfma_f32_32x32x16_bf16 v[2:17], v[102:105], v[98:101], v[2:17]
	v_lshl_add_u64 v[98:99], v[186:187], 0, s[16:17]
	v_add_co_u32_e32 v100, vcc, s52, v98
	v_lshl_add_u64 v[186:187], v[186:187], 0, s[90:91]
	s_nop 0
	v_addc_co_u32_e32 v101, vcc, 0, v99, vcc
	v_add_co_u32_e32 v102, vcc, s56, v98
	s_nop 1
	v_addc_co_u32_e32 v103, vcc, 0, v99, vcc
	global_store_short v[102:103], v0, off offset:-4096
	v_cvt_pk_bf16_f32 v0, v83, s0
	v_add_co_u32_e32 v82, vcc, s57, v98
	global_store_short v[100:101], v0, off offset:2048
	v_cvt_pk_bf16_f32 v0, v84, s0
	v_addc_co_u32_e32 v83, vcc, 0, v99, vcc
	global_store_short v[102:103], v0, off
	v_cvt_pk_bf16_f32 v0, v85, s0
	v_add_co_u32_e32 v84, vcc, s62, v98
	global_store_short v[102:103], v0, off offset:2048
	v_cvt_pk_bf16_f32 v0, v86, s0
	v_addc_co_u32_e32 v85, vcc, 0, v99, vcc
	global_store_short v[84:85], v0, off offset:-4096
	v_cvt_pk_bf16_f32 v0, v87, s0
	global_store_short v[82:83], v0, off offset:2048
	v_cvt_pk_bf16_f32 v0, v88, s0
	v_add_co_u32_e32 v82, vcc, s63, v98
	global_store_short v[84:85], v0, off
	v_cvt_pk_bf16_f32 v0, v89, s0
	v_addc_co_u32_e32 v83, vcc, 0, v99, vcc
	global_store_short v[84:85], v0, off offset:2048
	v_add_co_u32_e32 v84, vcc, s64, v98
	v_cvt_pk_bf16_f32 v0, v90, s0
	s_nop 0
	v_addc_co_u32_e32 v85, vcc, 0, v99, vcc
	global_store_short v[84:85], v0, off offset:-4096
	v_cvt_pk_bf16_f32 v0, v91, s0
	global_store_short v[82:83], v0, off offset:2048
	v_cvt_pk_bf16_f32 v0, v92, s0
	v_add_co_u32_e32 v82, vcc, s65, v98
	global_store_short v[84:85], v0, off
	v_cvt_pk_bf16_f32 v0, v93, s0
	v_addc_co_u32_e32 v83, vcc, 0, v99, vcc
	global_store_short v[84:85], v0, off offset:2048
	v_add_co_u32_e32 v84, vcc, s68, v98
	v_cvt_pk_bf16_f32 v0, v94, s0
	s_nop 0
	v_addc_co_u32_e32 v85, vcc, 0, v99, vcc
	global_store_short v[84:85], v0, off offset:-4096
	v_cvt_pk_bf16_f32 v0, v95, s0
	global_store_short v[82:83], v0, off offset:2048
	v_cvt_pk_bf16_f32 v0, v96, s0
	v_add_co_u32_e32 v82, vcc, s69, v98
	global_store_short v[84:85], v0, off
	v_cvt_pk_bf16_f32 v0, v97, s0
	v_addc_co_u32_e32 v83, vcc, 0, v99, vcc
	global_store_short v[84:85], v0, off offset:2048
	v_add_co_u32_e32 v84, vcc, s72, v98
	v_cvt_pk_bf16_f32 v0, v66, s0
	s_nop 0
	v_addc_co_u32_e32 v85, vcc, 0, v99, vcc
	global_store_short v[84:85], v0, off offset:-4096
	v_cvt_pk_bf16_f32 v0, v67, s0
	v_add_co_u32_e32 v66, vcc, s73, v98
	global_store_short v[82:83], v0, off offset:2048
	v_cvt_pk_bf16_f32 v0, v68, s0
	v_addc_co_u32_e32 v67, vcc, 0, v99, vcc
	global_store_short v[84:85], v0, off
	v_cvt_pk_bf16_f32 v0, v69, s0
	v_add_co_u32_e32 v68, vcc, s76, v98
	global_store_short v[84:85], v0, off offset:2048
	v_cvt_pk_bf16_f32 v0, v70, s0
	v_addc_co_u32_e32 v69, vcc, 0, v99, vcc
	global_store_short v[68:69], v0, off offset:-4096
	v_cvt_pk_bf16_f32 v0, v71, s0
	global_store_short v[66:67], v0, off offset:2048
	v_cvt_pk_bf16_f32 v0, v72, s0
	v_add_co_u32_e32 v66, vcc, s77, v98
	global_store_short v[68:69], v0, off
	v_cvt_pk_bf16_f32 v0, v73, s0
	v_addc_co_u32_e32 v67, vcc, 0, v99, vcc
	global_store_short v[68:69], v0, off offset:2048
	v_add_co_u32_e32 v68, vcc, s84, v98
	v_cvt_pk_bf16_f32 v0, v74, s0
	s_nop 0
	v_addc_co_u32_e32 v69, vcc, 0, v99, vcc
	global_store_short v[68:69], v0, off offset:-4096
	v_cvt_pk_bf16_f32 v0, v75, s0
	global_store_short v[66:67], v0, off offset:2048
	v_cvt_pk_bf16_f32 v0, v76, s0
	v_add_co_u32_e32 v66, vcc, s88, v98
	global_store_short v[68:69], v0, off
	v_cvt_pk_bf16_f32 v0, v77, s0
	v_addc_co_u32_e32 v67, vcc, 0, v99, vcc
	global_store_short v[68:69], v0, off offset:2048
	v_add_co_u32_e32 v68, vcc, s89, v98
	v_cvt_pk_bf16_f32 v0, v78, s0
	s_nop 0
	v_addc_co_u32_e32 v69, vcc, 0, v99, vcc
	global_store_short v[68:69], v0, off offset:-4096
	v_cvt_pk_bf16_f32 v0, v79, s0
	global_store_short v[66:67], v0, off offset:2048
	v_cvt_pk_bf16_f32 v0, v80, s0
	v_cmp_eq_u32_e32 vcc, 0, v183
	global_store_short v[68:69], v0, off
	v_cvt_pk_bf16_f32 v0, v81, s0
	s_and_b64 vcc, exec, vcc
	global_store_short v[68:69], v0, off offset:2048
	s_barrier
	s_waitcnt vmcnt(43)
	ds_write_b128 v174, v[106:109]
	s_waitcnt vmcnt(42)
	ds_write_b128 v174, v[110:113] offset:17408
	s_waitcnt vmcnt(41)
	ds_write_b128 v176, v[122:125] offset:34816
	s_waitcnt vmcnt(40)
	ds_write_b128 v178, v[126:129]
	s_waitcnt vmcnt(39)
	ds_write_b128 v178, v[130:133] offset:17408
	s_waitcnt vmcnt(38)
	ds_write_b128 v180, v[134:137] offset:34816
	s_waitcnt vmcnt(37)
	ds_write_b128 v182, v[138:141]
	s_waitcnt vmcnt(36)
	ds_write_b128 v182, v[142:145] offset:17408
	s_waitcnt vmcnt(35)
	ds_write_b128 v175, v[146:149] offset:34816
	ds_write_b128 v184, v[150:153]
	s_waitcnt vmcnt(34)
	ds_write_b128 v184, v[154:157] offset:17408
	ds_write_b128 v177, v[158:161] offset:34816
	s_waitcnt vmcnt(33)
	ds_write_b128 v176, v[162:165] offset:53248
	s_waitcnt vmcnt(32)
	ds_write_b128 v180, v[166:169] offset:53248
	s_waitcnt lgkmcnt(0)
	s_barrier
; DI void phase_scan_c(int wv_, int vb_, int nvb_, char* ws_, const Ctx& p, char* smem, int half) {
;     ...
;     }
;     ...
;     if (half == 0) {
; #pragma unroll
;       for (int mb = 0; mb < 4; ++mb)
; #pragma unroll
;         for (int i = 0; i < 16; ++i) stp[(mb * 16 + i) * 64] = S[mb][i];
;     }
	s_cbranch_vccz .LBB0_167
	s_waitcnt vmcnt(0)
	s_barrier
	v_readlane_b32 s0, v252, 17
	v_lshlrev_b32_e32 v0, 2, v216
	s_mov_b32 s52, 0x6600000
	v_add_u32_e32 v66, s0, v217
	v_ashrrev_i32_e32 v67, 31, v66
	v_lshlrev_b64 v[66:67], 14, v[66:67]
	v_lshl_add_u64 v[66:67], s[78:79], 0, v[66:67]
	v_lshl_add_u64 v[66:67], v[66:67], 0, v[0:1]
	s_mov_b64 s[0:1], 0x1eb00000
	v_add_co_u32_e32 v70, vcc, 0x1eb00000, v66
	v_lshl_add_u64 v[68:69], v[66:67], 0, s[0:1]
	s_nop 0
	v_addc_co_u32_e32 v71, vcc, 0, v67, vcc
	s_mov_b32 s0, 0x1eb01000
	global_store_dword v[70:71], v18, off
	global_store_dword v[68:69], v19, off offset:256
	global_store_dword v[68:69], v20, off offset:512
	global_store_dword v[68:69], v21, off offset:768
	global_store_dword v[68:69], v22, off offset:1024
	global_store_dword v[68:69], v23, off offset:1280
	global_store_dword v[68:69], v24, off offset:1536
	global_store_dword v[68:69], v25, off offset:1792
	global_store_dword v[68:69], v26, off offset:2048
	global_store_dword v[68:69], v27, off offset:2304
	global_store_dword v[68:69], v28, off offset:2560
	global_store_dword v[68:69], v29, off offset:2816
	global_store_dword v[68:69], v30, off offset:3072
	global_store_dword v[68:69], v31, off offset:3328
	global_store_dword v[68:69], v32, off offset:3584
	global_store_dword v[68:69], v33, off offset:3840
	v_add_co_u32_e32 v18, vcc, s0, v66
	s_mov_b32 s0, 0x1eb02000
	s_nop 0
	v_addc_co_u32_e32 v19, vcc, 0, v67, vcc
	v_add_co_u32_e32 v20, vcc, s0, v66
	s_mov_b32 s0, 0x1eb03000
	s_nop 0
	v_addc_co_u32_e32 v21, vcc, 0, v67, vcc
	global_store_dword v[20:21], v50, off offset:-4096
	global_store_dword v[18:19], v51, off offset:256
	global_store_dword v[18:19], v52, off offset:512
	global_store_dword v[18:19], v53, off offset:768
	global_store_dword v[18:19], v54, off offset:1024
	global_store_dword v[18:19], v55, off offset:1280
	global_store_dword v[18:19], v56, off offset:1536
	global_store_dword v[18:19], v57, off offset:1792
	global_store_dword v[18:19], v58, off offset:2048
	global_store_dword v[18:19], v59, off offset:2304
	global_store_dword v[18:19], v60, off offset:2560
	global_store_dword v[18:19], v61, off offset:2816
	global_store_dword v[18:19], v62, off offset:3072
	global_store_dword v[18:19], v63, off offset:3328
	global_store_dword v[18:19], v64, off offset:3584
	global_store_dword v[18:19], v65, off offset:3840
	global_store_dword v[20:21], v34, off
	global_store_dword v[20:21], v35, off offset:256
	global_store_dword v[20:21], v36, off offset:512
	global_store_dword v[20:21], v37, off offset:768
	global_store_dword v[20:21], v38, off offset:1024
	global_store_dword v[20:21], v39, off offset:1280
	global_store_dword v[20:21], v40, off offset:1536
	global_store_dword v[20:21], v41, off offset:1792
	global_store_dword v[20:21], v42, off offset:2048
	global_store_dword v[20:21], v43, off offset:2304
	global_store_dword v[20:21], v44, off offset:2560
	global_store_dword v[20:21], v45, off offset:2816
	global_store_dword v[20:21], v46, off offset:3072
	global_store_dword v[20:21], v47, off offset:3328
	global_store_dword v[20:21], v48, off offset:3584
	global_store_dword v[20:21], v49, off offset:3840
	v_add_co_u32_e32 v18, vcc, s0, v66
	s_nop 1
	v_addc_co_u32_e32 v19, vcc, 0, v67, vcc
	global_store_dword v[18:19], v2, off
	global_store_dword v[18:19], v3, off offset:256
	global_store_dword v[18:19], v4, off offset:512
	global_store_dword v[18:19], v5, off offset:768
	global_store_dword v[18:19], v6, off offset:1024
	global_store_dword v[18:19], v7, off offset:1280
	global_store_dword v[18:19], v8, off offset:1536
	global_store_dword v[18:19], v9, off offset:1792
	global_store_dword v[18:19], v10, off offset:2048
	global_store_dword v[18:19], v11, off offset:2304
	global_store_dword v[18:19], v12, off offset:2560
	global_store_dword v[18:19], v13, off offset:2816
	global_store_dword v[18:19], v14, off offset:3072
	global_store_dword v[18:19], v15, off offset:3328
	global_store_dword v[18:19], v16, off offset:3584
	global_store_dword v[18:19], v17, off offset:3840

; DI void phase_outnorm_c(int wv_, int vb_, int nvb_, char* ws_, const Ctx& p) {
;   u16* O = (u16*)(ws_ + WS_H); const u16* G = (const u16*)(ws_ + WS_CG);
;   const int tid = tidx(wv_); const int e = tid & 15;
;   float og[8];
; #pragma unroll
;   for (int j = 0; j < 8; ++j) og[j] = p.c_o_gain[e * 8 + j];
;   const size_t stride = (size_t)nvb_ * 256, total = (size_t)NTOK * 8 * 16;
;   for (size_t idx0 = (size_t)vb_ * 256 + tid; idx0 < total; idx0 += 4 * stride) {
;     bf16x8 ov[4], gv[4]; bool ok[4];
; #pragma unroll
;     for (int q = 0; q < 4; ++q) { const size_t idx = idx0 + q * stride; ok[q] = idx < total; const size_t rowh = (ok[q] ? idx : idx0) >> 4;
;       ov[q] = *(const bf16x8*)(O + rowh * 128 + e * 8); gv[q] = *(const bf16x8*)(G + rowh * 128 + e * 8); }
.LBB0_211:
	s_andn2_b64 vcc, exec, s[2:3]
	s_cbranch_vccnz .LBB0_235
	s_cmp_gt_i32 s23, 8
	s_mov_b64 s[2:3], -1
	s_cbranch_scc0 .LBB0_223
	s_mov_b64 s[2:3], 0
	s_branch .LBB0_223
	s_mov_b32 s0, s33
	v_mov_b32_e32 v0, v204
	s_nop 0
	v_lshl_or_b32 v12, s0, 6, v0
	v_readlane_b32 s0, v254, 8
	v_ashrrev_i32_e32 v13, 31, v12
	v_readlane_b32 s1, v254, 9
	s_nop 1
	v_lshl_add_u64 v[10:11], s[0:1], 0, v[12:13]
	s_mov_b64 s[0:1], 0x400000
	v_cmp_gt_u64_e32 vcc, s[0:1], v[10:11]
	s_and_saveexec_b64 s[8:9], vcc
	s_cbranch_execz .LBB0_222
	v_lshlrev_b32_e32 v0, 3, v0
	v_and_b32_e32 v0, 0x78, v0
	v_lshlrev_b32_e32 v6, 2, v0
	global_load_dwordx4 v[2:5], v6, s[14:15] offset:16
	s_nop 0
	global_load_dwordx4 v[6:9], v6, s[14:15]
	v_lshlrev_b32_e32 v0, 1, v0
	v_lshl_add_u64 v[14:15], s[78:79], 0, v[0:1]
	s_mov_b64 s[0:1], 0x19600000
	v_lshl_add_u64 v[32:33], v[14:15], 0, s[0:1]
	v_readlane_b32 s0, v253, 38
	v_readlane_b32 s1, v253, 39
	v_lshl_add_u64 v[30:31], s[82:83], 0, v[0:1]
	s_mov_b64 s[10:11], 0
	v_lshl_add_u64 v[34:35], v[12:13], 3, s[0:1]
	s_branch .LBB0_216

; DI void phase_scan_c(int wv_, int vb_, int nvb_, char* ws_, const Ctx& p, char* smem, int half) {
;     ...
;   if ((vb_ >> 1) < 64 && (vb_ & 1)) { for (int q_ = 0; q_ < 66; ++q_) __syncthreads(); }
; DI void phase_outnorm_c(int wv_, int vb_, int nvb_, char* ws_, const Ctx& p) {
;   u16* O = (u16*)(ws_ + WS_H); const u16* G = (const u16*)(ws_ + WS_CG);
;   const int tid = tidx(wv_); const int e = tid & 15;
;   float og[8];
; #pragma unroll
;   for (int j = 0; j < 8; ++j) og[j] = p.c_o_gain[e * 8 + j];
.LBB0_223:
	s_andn2_b64 vcc, exec, s[2:3]
	s_cbranch_vccnz .LBB0_235
	v_readlane_b32 s2, v252, 13
	v_readlane_b32 s3, v252, 14
	s_mov_b32 s1, s33
	v_mov_b32_e32 v82, v204
	s_andn2_b64 vcc, exec, s[2:3]
	s_cbranch_vccnz .LBB0_227
	v_lshl_or_b32 v10, s33, 6, v204
	v_and_b32_e32 v11, 15, v10
	v_lshrrev_b32_e32 v12, 4, v10
	v_readlane_b32 s2, v254, 14
	s_lshr_b32 s2, s2, 1
	s_and_b32 s3, s2, 7
	s_lshr_b32 s2, s2, 3
	s_lshl_b32 s2, s2, 12
	v_readlane_b32 s4, v255, 1
	s_lshl_b32 s4, s4, 11
	s_add_i32 s2, s2, s4
	s_lshl_b32 s2, s2, 3
	s_add_i32 s2, s2, s3
	s_lshl_b32 s2, s2, 8
	v_lshlrev_b32_e32 v13, 11, v12
	v_lshl_add_u32 v13, v11, 4, v13
	v_add_u32_e32 v13, s2, v13
	s_add_u32 s6, s78, 0x19600000
	s_addc_u32 s7, s79, 0
	s_mov_b64 s[4:5], s[82:83]
	v_readlane_b32 s8, v254, 28
	v_readlane_b32 s9, v254, 29
	v_lshlrev_b32_e32 v14, 5, v11
	s_nop 3
	global_load_dwordx4 v[2:5], v14, s[8:9]
	global_load_dwordx4 v[6:9], v14, s[8:9] offset:16
	s_waitcnt vmcnt(0)
	s_barrier
	s_barrier
	s_mov_b32 s10, 0

; DI void phase_scan_c(int wv_, int vb_, int nvb_, char* ws_, const Ctx& p, char* smem, int half) {
;     ...
;   if ((vb_ >> 1) < 64 && (vb_ & 1)) { for (int q_ = 0; q_ < 66; ++q_) __syncthreads(); }
;   if ((vb_ >> 1) < 64 && !(vb_ & 1)) {
.Lonc_done:
	s_nop 0
	s_nop 0
	s_nop 0
	s_nop 0
	s_nop 0
	s_nop 0
	s_nop 0
	s_nop 0
	s_nop 0
	s_waitcnt vmcnt(0)
	s_mov_b32 s1, s33
	v_mov_b32_e32 v82, v204

; #define MFMA32(a, b, c) __builtin_amdgcn_mfma_f32_32x32x16_bf16((a), (b), (c), 0, 0, 0)
; DI void phase_scan_c(int wv_, int vb_, int nvb_, char* ws_, const Ctx& p, char* smem, int half) {
;     ...
;     for (int nc = 0; nc < 32; ++nc) {
;       const size_t uix = (size_t)blk * 32 + nc;
;       const float egl = GL[uix];
;       bf16x8 ucur[4];
; #pragma unroll
;       for (int tb = 0; tb < 2; ++tb) { ucur[2 * tb] = *(const bf16x8*)(CU + (uix * 128 + dv0 + c) * 64 + h * 16 + tb * 32); ucur[2 * tb + 1] = *(const bf16x8*)(CU + (uix * 128 + dv0 + c) * 64 + h * 16 + tb * 32 + 8); }
;       const u16* Wp = sW + c * 136 + h * 8;
;       const u16* Qp = sQ + c * 136 + h * 8;
;       const u16* KTp = sKT + c * 72 + h * 8;
;       const u16* QKp = sQK + c * 72 + h * 8;
;       f32x16 X[2], Oa[2];
;       X[0] = zero16(); X[1] = zero16(); Oa[0] = zero16(); Oa[1] = zero16();
; #pragma unroll
;       for (int mb = 0; mb < 4; ++mb) {
; #pragma unroll
;         for (int s = 0; s < 2; ++s) {
;           const bf16x8 sb = pack8(S[mb], s);
; #pragma unroll
;           for (int tb = 0; tb < 2; ++tb) {
;             bf16x8 a = *(const bf16x8*)(Wp + tb * 32 * 136 + mb * 32 + s * 16);
;             bf16x8 a2 = *(const bf16x8*)(Qp + tb * 32 * 136 + mb * 32 + s * 16);
;             X[tb] = MFMA32(a, sb, X[tb]);
;             Oa[tb] = MFMA32(a2, sb, Oa[tb]);
;           }
;         }
;       }
.LBB0_232:
	s_add_u32 s12, s4, s16
	s_addc_u32 s13, s5, s17
	v_lshl_add_u64 v[2:3], v[186:187], 0, s[16:17]
	global_load_dword v0, v1, s[12:13]
	global_load_dwordx4 v[144:147], v[2:3], off offset:-64
	global_load_dwordx4 v[10:13], v[2:3], off offset:-48
	global_load_dwordx4 v[6:9], v[2:3], off
	s_nop 0
	global_load_dwordx4 v[2:5], v[2:3], off offset:16
	ds_read_b128 v[84:87], v216 offset:17408
	ds_read_b128 v[88:91], v216
	ds_read_b128 v[148:151], v216 offset:32
	v_cvt_pk_bf16_f32 v80, v16, v17
	v_cvt_pk_bf16_f32 v81, v18, v19
	v_cvt_pk_bf16_f32 v82, v20, v21
	v_cvt_pk_bf16_f32 v83, v22, v23
	v_cvt_pk_bf16_f32 v152, v24, v25
	v_cvt_pk_bf16_f32 v153, v26, v27
	s_waitcnt lgkmcnt(1)
	v_mfma_f32_32x32x16_bf16 v[128:143], v[88:91], v[80:83], 0
	v_cvt_pk_bf16_f32 v154, v28, v29
	v_cvt_pk_bf16_f32 v155, v30, v31
	v_add_co_u32_e64 v218, s[12:13], s1, 1
	s_add_i32 s1, s1, 33
	s_and_b64 s[12:13], s[12:13], exec
	s_cselect_b32 s1, 31, s1
	v_mfma_f32_32x32x16_bf16 v[96:111], v[84:87], v[80:83], 0
	ds_read_b128 v[84:87], v216 offset:8704
	ds_read_b128 v[88:91], v216 offset:26112
	ds_read_b128 v[156:159], v216 offset:17440
	s_add_u32 s12, s56, s1
	s_addc_u32 s13, s57, 0
	s_lshl_b64 s[18:19], s[12:13], 13
	s_lshl_b64 s[12:13], s[12:13], 14
	s_add_u32 s34, s6, s12
	s_waitcnt lgkmcnt(2)
	v_mfma_f32_32x32x16_bf16 v[112:127], v[84:87], v[80:83], 0
	s_addc_u32 s35, s7, s13
	s_add_u32 s44, s8, s12
	s_addc_u32 s45, s9, s13
	s_add_u32 s12, s10, s12
	s_addc_u32 s13, s11, s13
	v_lshl_add_u64 v[160:161], s[12:13], 0, v[200:201]
	v_readfirstlane_b32 s0, v218
	s_waitcnt lgkmcnt(1)
	v_mfma_f32_32x32x16_bf16 v[80:95], v[88:91], v[80:83], 0
	v_lshl_add_u64 v[186:187], v[186:187], 0, s[2:3]
	s_mov_b32 s1, s0
	s_waitcnt vmcnt(4)
	v_mul_f32_e64 v30, v30, v0
	v_mul_f32_e64 v31, v31, v0
	v_mfma_f32_32x32x16_bf16 v[128:143], v[148:151], v[152:155], v[128:143]
	v_mul_f32_e64 v28, v28, v0
	v_mul_f32_e64 v29, v29, v0
	v_mul_f32_e64 v26, v26, v0
	v_mul_f32_e64 v27, v27, v0
	v_mul_f32_e64 v24, v24, v0
	v_mul_f32_e64 v25, v25, v0
	v_pk_mul_f32 v[22:23], v[22:23], v[0:1] op_sel_hi:[1,0]
	v_pk_mul_f32 v[20:21], v[20:21], v[0:1] op_sel_hi:[1,0]
	v_pk_mul_f32 v[18:19], v[18:19], v[0:1] op_sel_hi:[1,0]
	v_pk_mul_f32 v[16:17], v[16:17], v[0:1] op_sel_hi:[1,0]
	s_waitcnt lgkmcnt(0)
	v_mfma_f32_32x32x16_bf16 v[96:111], v[156:159], v[152:155], v[96:111]
	ds_read_b128 v[148:151], v216 offset:8736
	ds_read_b128 v[156:159], v216 offset:26144
	s_waitcnt lgkmcnt(1)
	v_mfma_f32_32x32x16_bf16 v[112:127], v[148:151], v[152:155], v[112:127]
	v_cvt_pk_bf16_f32 v148, v32, v33
	v_cvt_pk_bf16_f32 v149, v34, v35
	v_cvt_pk_bf16_f32 v150, v36, v37
	v_cvt_pk_bf16_f32 v151, v38, v39
	v_mul_f32_e64 v38, v38, v0
	v_mul_f32_e64 v39, v39, v0
	v_pk_mul_f32 v[36:37], v[36:37], v[0:1] op_sel_hi:[1,0]
	v_pk_mul_f32 v[34:35], v[34:35], v[0:1] op_sel_hi:[1,0]
	s_waitcnt lgkmcnt(0)
	v_mfma_f32_32x32x16_bf16 v[80:95], v[156:159], v[152:155], v[80:95]
	ds_read_b128 v[152:155], v216 offset:64
	ds_read_b128 v[156:159], v216 offset:17472
	v_mul_f32_e64 v32, v32, v0
	v_mul_f32_e64 v33, v33, v0
	s_waitcnt lgkmcnt(1)
	v_mfma_f32_32x32x16_bf16 v[128:143], v[152:155], v[148:151], v[128:143]
	s_waitcnt lgkmcnt(0)
	v_mfma_f32_32x32x16_bf16 v[96:111], v[156:159], v[148:151], v[96:111]
	ds_read_b128 v[152:155], v216 offset:8768
	ds_read_b128 v[156:159], v216 offset:26176
	s_waitcnt lgkmcnt(1)
	v_mfma_f32_32x32x16_bf16 v[112:127], v[152:155], v[148:151], v[112:127]
	s_waitcnt lgkmcnt(0)
	v_mfma_f32_32x32x16_bf16 v[80:95], v[156:159], v[148:151], v[80:95]
	ds_read_b128 v[152:155], v216 offset:96
	ds_read_b128 v[156:159], v216 offset:17504
	v_cvt_pk_bf16_f32 v148, v40, v41
	v_cvt_pk_bf16_f32 v149, v42, v43
	v_cvt_pk_bf16_f32 v150, v44, v45
	v_cvt_pk_bf16_f32 v151, v46, v47
	v_pk_mul_f32 v[46:47], v[46:47], v[0:1] op_sel_hi:[1,0]
	v_pk_mul_f32 v[44:45], v[44:45], v[0:1] op_sel_hi:[1,0]
	s_waitcnt lgkmcnt(1)
	v_mfma_f32_32x32x16_bf16 v[128:143], v[152:155], v[148:151], v[128:143]
	v_mul_f32_e64 v42, v42, v0
	v_mul_f32_e64 v43, v43, v0
	v_mul_f32_e64 v40, v40, v0
	v_mul_f32_e64 v41, v41, v0
	s_waitcnt lgkmcnt(0)
	v_mfma_f32_32x32x16_bf16 v[96:111], v[156:159], v[148:151], v[96:111]
	ds_read_b128 v[152:155], v216 offset:8800
	ds_read_b128 v[156:159], v216 offset:26208
	s_waitcnt lgkmcnt(1)
	v_mfma_f32_32x32x16_bf16 v[112:127], v[152:155], v[148:151], v[112:127]
	s_waitcnt lgkmcnt(0)
	v_mfma_f32_32x32x16_bf16 v[80:95], v[156:159], v[148:151], v[80:95]
	ds_read_b128 v[152:155], v216 offset:128
	ds_read_b128 v[156:159], v216 offset:17536
	v_cvt_pk_bf16_f32 v148, v48, v49
	v_cvt_pk_bf16_f32 v149, v50, v51
	v_cvt_pk_bf16_f32 v150, v52, v53
	v_cvt_pk_bf16_f32 v151, v54, v55
	v_pk_mul_f32 v[54:55], v[54:55], v[0:1] op_sel_hi:[1,0]
	v_pk_mul_f32 v[52:53], v[52:53], v[0:1] op_sel_hi:[1,0]
	s_waitcnt lgkmcnt(1)
	v_mfma_f32_32x32x16_bf16 v[128:143], v[152:155], v[148:151], v[128:143]
	v_mul_f32_e64 v50, v50, v0
	v_mul_f32_e64 v51, v51, v0
	v_mul_f32_e64 v48, v48, v0
	v_mul_f32_e64 v49, v49, v0
	s_waitcnt lgkmcnt(0)
	v_mfma_f32_32x32x16_bf16 v[96:111], v[156:159], v[148:151], v[96:111]
	ds_read_b128 v[152:155], v216 offset:8832
	ds_read_b128 v[156:159], v216 offset:26240
	s_waitcnt lgkmcnt(1)
	v_mfma_f32_32x32x16_bf16 v[112:127], v[152:155], v[148:151], v[112:127]
	s_waitcnt lgkmcnt(0)
	v_mfma_f32_32x32x16_bf16 v[80:95], v[156:159], v[148:151], v[80:95]
	ds_read_b128 v[152:155], v216 offset:160
	ds_read_b128 v[156:159], v216 offset:17568
	v_cvt_pk_bf16_f32 v148, v56, v57
	v_cvt_pk_bf16_f32 v149, v58, v59
	v_cvt_pk_bf16_f32 v150, v60, v61
	v_cvt_pk_bf16_f32 v151, v62, v63
	v_pk_mul_f32 v[62:63], v[62:63], v[0:1] op_sel_hi:[1,0]
	v_pk_mul_f32 v[60:61], v[60:61], v[0:1] op_sel_hi:[1,0]
	s_waitcnt lgkmcnt(1)
; #define MFMA32(a, b, c) __builtin_amdgcn_mfma_f32_32x32x16_bf16((a), (b), (c), 0, 0, 0)
; DI float bfs(short v) { return __uint_as_float(((unsigned)(u16)v) << 16); }
; DI void phase_scan_c(int wv_, int vb_, int nvb_, char* ws_, const Ctx& p, char* smem, int half) {
;     ...
; #pragma unroll
;       for (int mb = 0; mb < 4; ++mb) {
; #pragma unroll
;         for (int s = 0; s < 2; ++s) {
;           const bf16x8 sb = pack8(S[mb], s);
; #pragma unroll
;           for (int tb = 0; tb < 2; ++tb) {
;             bf16x8 a = *(const bf16x8*)(Wp + tb * 32 * 136 + mb * 32 + s * 16);
;             bf16x8 a2 = *(const bf16x8*)(Qp + tb * 32 * 136 + mb * 32 + s * 16);
;             X[tb] = MFMA32(a, sb, X[tb]);
;             Oa[tb] = MFMA32(a2, sb, Oa[tb]);
;           }
;         }
;       }
;       bf16x8 vb[2][2];
; #pragma unroll
;       for (int tb = 0; tb < 2; ++tb) {
; #pragma unroll
;         for (int i = 0; i < 8; ++i) { X[tb][i] = bfs(ucur[2 * tb][i]) - X[tb][i]; X[tb][8 + i] = bfs(ucur[2 * tb + 1][i]) - X[tb][8 + i]; }
;         vb[tb][0] = pack8(X[tb], 0); vb[tb][1] = pack8(X[tb], 1);
	v_mfma_f32_32x32x16_bf16 v[128:143], v[152:155], v[148:151], v[128:143]
	v_mul_f32_e64 v58, v58, v0
	v_mul_f32_e64 v59, v59, v0
	v_mul_f32_e64 v56, v56, v0
	v_mul_f32_e64 v57, v57, v0
	s_waitcnt lgkmcnt(0)
	v_mfma_f32_32x32x16_bf16 v[96:111], v[156:159], v[148:151], v[96:111]
	ds_read_b128 v[152:155], v216 offset:8864
	ds_read_b128 v[156:159], v216 offset:26272
	s_waitcnt lgkmcnt(1)
	v_mfma_f32_32x32x16_bf16 v[112:127], v[152:155], v[148:151], v[112:127]
	s_waitcnt lgkmcnt(0)
	v_mfma_f32_32x32x16_bf16 v[80:95], v[156:159], v[148:151], v[80:95]
	ds_read_b128 v[152:155], v216 offset:192
	ds_read_b128 v[156:159], v216 offset:17600
	v_cvt_pk_bf16_f32 v148, v64, v65
	v_cvt_pk_bf16_f32 v149, v66, v67
	v_cvt_pk_bf16_f32 v150, v68, v69
	v_cvt_pk_bf16_f32 v151, v70, v71
	v_pk_mul_f32 v[70:71], v[70:71], v[0:1] op_sel_hi:[1,0]
	v_pk_mul_f32 v[68:69], v[68:69], v[0:1] op_sel_hi:[1,0]
	s_waitcnt lgkmcnt(1)
	v_mfma_f32_32x32x16_bf16 v[128:143], v[152:155], v[148:151], v[128:143]
	v_mul_f32_e64 v66, v66, v0
	v_mul_f32_e64 v67, v67, v0
	v_mul_f32_e64 v64, v64, v0
	v_mul_f32_e64 v65, v65, v0
	s_waitcnt lgkmcnt(0)
	v_mfma_f32_32x32x16_bf16 v[96:111], v[156:159], v[148:151], v[96:111]
	ds_read_b128 v[152:155], v216 offset:8896
	ds_read_b128 v[156:159], v216 offset:26304
	s_waitcnt lgkmcnt(1)
	v_mfma_f32_32x32x16_bf16 v[112:127], v[152:155], v[148:151], v[112:127]
	s_waitcnt lgkmcnt(0)
	v_mfma_f32_32x32x16_bf16 v[80:95], v[156:159], v[148:151], v[80:95]
	ds_read_b128 v[152:155], v216 offset:224
	ds_read_b128 v[156:159], v216 offset:17632
	v_cvt_pk_bf16_f32 v148, v72, v73
	v_cvt_pk_bf16_f32 v149, v74, v75
	v_cvt_pk_bf16_f32 v150, v76, v77
	v_cvt_pk_bf16_f32 v151, v78, v79
	v_pk_mul_f32 v[78:79], v[78:79], v[0:1] op_sel_hi:[1,0]
	v_pk_mul_f32 v[76:77], v[76:77], v[0:1] op_sel_hi:[1,0]
	s_waitcnt lgkmcnt(1)
	v_mfma_f32_32x32x16_bf16 v[128:143], v[152:155], v[148:151], v[128:143]
	v_mul_f32_e64 v74, v74, v0
	v_mul_f32_e64 v75, v75, v0
	v_mul_f32_e64 v72, v72, v0
	v_mul_f32_e64 v73, v73, v0
	s_waitcnt lgkmcnt(0)
	v_mfma_f32_32x32x16_bf16 v[96:111], v[156:159], v[148:151], v[96:111]
	ds_read_b128 v[152:155], v216 offset:8928
	ds_read_b128 v[156:159], v216 offset:26336
	ds_read_b128 v[220:223], v217 offset:53248
	global_load_dwordx4 v[160:163], v[160:161], off
	s_waitcnt lgkmcnt(2)
	v_mfma_f32_32x32x16_bf16 v[112:127], v[152:155], v[148:151], v[112:127]
	v_lshl_add_u64 v[152:153], s[34:35], 0, v[200:201]
	global_load_dwordx4 v[152:155], v[152:153], off
	s_waitcnt lgkmcnt(1)
	v_mfma_f32_32x32x16_bf16 v[80:95], v[156:159], v[148:151], v[80:95]
	s_waitcnt vmcnt(5)
	v_and_b32_e32 v149, 0xffff0000, v144
	v_lshlrev_b32_e32 v148, 16, v144
	v_add_f32_e64 v128, v148, -v128
	v_add_f32_e64 v129, v149, -v129
	s_waitcnt vmcnt(4)
	v_and_b32_e32 v149, 0xffff0000, v10
	v_lshlrev_b32_e32 v148, 16, v10
	v_pk_add_f32 v[136:137], v[148:149], v[136:137] neg_lo:[0,1] neg_hi:[0,1]
	v_and_b32_e32 v149, 0xffff0000, v145
	v_lshlrev_b32_e32 v148, 16, v145
	v_and_b32_e32 v145, 0xffff0000, v11
	v_lshlrev_b32_e32 v144, 16, v11
	v_and_b32_e32 v11, 0xffff0000, v146
	v_lshlrev_b32_e32 v10, 16, v146
	v_pk_add_f32 v[10:11], v[10:11], v[132:133] neg_lo:[0,1] neg_hi:[0,1]
	v_and_b32_e32 v133, 0xffff0000, v12
	v_lshlrev_b32_e32 v132, 16, v12
	v_pk_add_f32 v[132:133], v[132:133], v[140:141] neg_lo:[0,1] neg_hi:[0,1]
	v_and_b32_e32 v141, 0xffff0000, v147
	v_lshlrev_b32_e32 v140, 16, v147
	v_pk_add_f32 v[130:131], v[148:149], v[130:131] neg_lo:[0,1] neg_hi:[0,1]
	v_pk_add_f32 v[134:135], v[140:141], v[134:135] neg_lo:[0,1] neg_hi:[0,1]
	v_cvt_pk_bf16_f32 v128, v128, v129
	v_cvt_pk_bf16_f32 v129, v130, v131
	v_cvt_pk_bf16_f32 v130, v10, v11
	v_cvt_pk_bf16_f32 v131, v134, v135
	v_and_b32_e32 v141, 0xffff0000, v13
	v_lshlrev_b32_e32 v140, 16, v13
	s_waitcnt lgkmcnt(0)
	v_mfma_f32_32x32x16_bf16 v[96:111], v[220:223], v[128:131], v[96:111]
	ds_read_b128 v[220:223], v217 offset:53280
	v_add_f32_e64 v138, v144, -v138
	v_add_f32_e64 v139, v145, -v139
	v_add_f32_e64 v140, v140, -v142
	v_add_f32_e64 v141, v141, -v143
	v_cvt_pk_bf16_f32 v10, v136, v137
	v_cvt_pk_bf16_f32 v11, v138, v139
	v_cvt_pk_bf16_f32 v12, v132, v133
	v_cvt_pk_bf16_f32 v13, v140, v141
	s_waitcnt vmcnt(3)
	v_and_b32_e32 v133, 0xffff0000, v6
	v_lshlrev_b32_e32 v132, 16, v6
	s_waitcnt lgkmcnt(0)
	v_mfma_f32_32x32x16_bf16 v[96:111], v[220:223], v[10:13], v[96:111]
	ds_read_b128 v[220:223], v217 offset:53312
	v_add_f32_e64 v112, v132, -v112
	v_add_f32_e64 v113, v133, -v113
	s_waitcnt vmcnt(2)
	v_and_b32_e32 v133, 0xffff0000, v2
	v_lshlrev_b32_e32 v132, 16, v2
	v_pk_add_f32 v[120:121], v[132:133], v[120:121] neg_lo:[0,1] neg_hi:[0,1]
	v_and_b32_e32 v133, 0xffff0000, v7
	v_lshlrev_b32_e32 v132, 16, v7
	v_and_b32_e32 v7, 0xffff0000, v3
	v_lshlrev_b32_e32 v6, 16, v3
	v_pk_add_f32 v[122:123], v[6:7], v[122:123] neg_lo:[0,1] neg_hi:[0,1]
	v_and_b32_e32 v3, 0xffff0000, v8
	v_lshlrev_b32_e32 v2, 16, v8
	v_and_b32_e32 v7, 0xffff0000, v4
	v_lshlrev_b32_e32 v6, 16, v4
	v_pk_add_f32 v[2:3], v[2:3], v[116:117] neg_lo:[0,1] neg_hi:[0,1]
	v_pk_add_f32 v[116:117], v[6:7], v[124:125] neg_lo:[0,1] neg_hi:[0,1]
	v_and_b32_e32 v7, 0xffff0000, v9
	v_lshlrev_b32_e32 v6, 16, v9
	v_pk_add_f32 v[114:115], v[132:133], v[114:115] neg_lo:[0,1] neg_hi:[0,1]
	v_pk_add_f32 v[118:119], v[6:7], v[118:119] neg_lo:[0,1] neg_hi:[0,1]
	v_and_b32_e32 v7, 0xffff0000, v5
	v_lshlrev_b32_e32 v6, 16, v5
	v_pk_add_f32 v[124:125], v[6:7], v[126:127] neg_lo:[0,1] neg_hi:[0,1]
	v_cvt_pk_bf16_f32 v6, v112, v113
	v_cvt_pk_bf16_f32 v7, v114, v115
	v_cvt_pk_bf16_f32 v8, v2, v3
	v_cvt_pk_bf16_f32 v9, v118, v119
	v_cvt_pk_bf16_f32 v2, v120, v121
	v_cvt_pk_bf16_f32 v3, v122, v123
	s_waitcnt lgkmcnt(0)
; #define MFMA32(a, b, c) __builtin_amdgcn_mfma_f32_32x32x16_bf16((a), (b), (c), 0, 0, 0)
; DI void phase_scan_c(int wv_, int vb_, int nvb_, char* ws_, const Ctx& p, char* smem, int half) {
;     ...
;       { const int ncn = nc < 31 ? nc + 1 : 31; SLOAD((size_t)blk * 32 + ncn) }
; #pragma unroll
;       for (int tb = 0; tb < 2; ++tb)
; #pragma unroll
;         for (int tb2 = 0; tb2 < 2; ++tb2)
; #pragma unroll
;           for (int s = 0; s < 2; ++s) {
;             bf16x8 a = *(const bf16x8*)(QKp + tb * 32 * 72 + tb2 * 32 + s * 16);
;             Oa[tb] = MFMA32(a, vb[tb2][s], Oa[tb]);
;           }
; #pragma unroll
;       for (int mb = 0; mb < 4; ++mb) {
; #pragma unroll
;         for (int i = 0; i < 16; ++i) S[mb][i] *= egl;
; #pragma unroll
;         for (int tb = 0; tb < 2; ++tb)
; #pragma unroll
;           for (int s = 0; s < 2; ++s) {
;             bf16x8 a = *(const bf16x8*)(KTp + mb * 32 * 72 + tb * 32 + s * 16);
;             S[mb] = MFMA32(a, vb[tb][s], S[mb]);
;           }
;       }
	v_mfma_f32_32x32x16_bf16 v[96:111], v[220:223], v[6:9], v[96:111]
	ds_read_b128 v[220:223], v217 offset:53344
	v_cvt_pk_bf16_f32 v4, v116, v117
	v_cvt_pk_bf16_f32 v5, v124, v125
	v_lshl_add_u64 v[120:121], s[12:13], 0, v[188:189]
	v_lshl_add_u64 v[136:137], s[12:13], 0, v[190:191]
	v_lshl_add_u64 v[148:149], s[12:13], 0, v[192:193]
	s_add_u32 s12, s14, s18
	s_waitcnt lgkmcnt(0)
	v_mfma_f32_32x32x16_bf16 v[96:111], v[220:223], v[2:5], v[96:111]
	ds_read_b128 v[220:223], v217 offset:57856
	s_addc_u32 s13, s15, s19
	v_lshl_add_u64 v[112:113], s[34:35], 0, v[188:189]
	v_lshl_add_u64 v[116:117], s[44:45], 0, v[188:189]
	v_lshl_add_u64 v[124:125], s[34:35], 0, v[190:191]
	v_lshl_add_u64 v[132:133], s[44:45], 0, v[190:191]
	v_lshl_add_u64 v[140:141], s[34:35], 0, v[192:193]
	s_waitcnt lgkmcnt(0)
	v_mfma_f32_32x32x16_bf16 v[80:95], v[220:223], v[128:131], v[80:95]
	ds_read_b128 v[220:223], v217 offset:57888
	v_lshl_add_u64 v[144:145], s[44:45], 0, v[192:193]
	v_lshl_add_u64 v[156:157], s[44:45], 0, v[200:201]
	v_lshl_add_u64 v[164:165], s[12:13], 0, v[14:15]
	v_lshl_add_u64 v[168:169], s[12:13], 0, v[174:175]
	global_load_dwordx4 v[112:115], v[112:113], off
	v_cvt_pk_bf16_f32 v0, v96, s0
	s_waitcnt lgkmcnt(0)
	v_mfma_f32_32x32x16_bf16 v[80:95], v[220:223], v[10:13], v[80:95]
	ds_read_b128 v[220:223], v217 offset:57920
	global_load_dwordx4 v[116:119], v[116:117], off
	s_add_u32 s4, s4, 4
	global_load_dwordx4 v[120:123], v[120:121], off
	s_addc_u32 s5, s5, 0
	global_load_dwordx4 v[124:127], v[124:125], off
	s_waitcnt lgkmcnt(0)
	v_mfma_f32_32x32x16_bf16 v[80:95], v[220:223], v[6:9], v[80:95]
	ds_read_b128 v[220:223], v217 offset:57952
	global_load_dwordx4 v[132:135], v[132:133], off
	s_nop 0
	global_load_dwordx4 v[136:139], v[136:137], off
	s_nop 0
	global_load_dwordx4 v[140:143], v[140:141], off
	s_nop 0
	global_load_dwordx4 v[144:147], v[144:145], off
	s_waitcnt lgkmcnt(0)
	v_mfma_f32_32x32x16_bf16 v[80:95], v[220:223], v[2:5], v[80:95]
	global_load_dwordx4 v[148:151], v[148:149], off
	s_nop 0
	global_load_dwordx4 v[156:159], v[156:157], off
	s_nop 0
	global_load_dwordx4 v[164:167], v[164:165], off
	s_nop 0
	global_load_dwordx4 v[168:171], v[168:169], off
	ds_read_b128 v[220:223], v217 offset:34816
	ds_read_b128 v[224:227], v217 offset:34848
	s_waitcnt lgkmcnt(1)
	v_mfma_f32_32x32x16_bf16 v[16:31], v[220:223], v[128:131], v[16:31]
	ds_read_b128 v[220:223], v217 offset:34880
	s_waitcnt lgkmcnt(1)
	v_mfma_f32_32x32x16_bf16 v[16:31], v[224:227], v[10:13], v[16:31]
	s_waitcnt lgkmcnt(0)
	v_mfma_f32_32x32x16_bf16 v[16:31], v[220:223], v[6:9], v[16:31]
	ds_read_b128 v[220:223], v217 offset:34912
	s_waitcnt lgkmcnt(0)
	v_mfma_f32_32x32x16_bf16 v[16:31], v[220:223], v[2:5], v[16:31]
	ds_read_b128 v[220:223], v217 offset:39424
	s_waitcnt lgkmcnt(0)
	v_mfma_f32_32x32x16_bf16 v[32:47], v[220:223], v[128:131], v[32:47]
	ds_read_b128 v[220:223], v217 offset:39456
	s_waitcnt lgkmcnt(0)
	v_mfma_f32_32x32x16_bf16 v[32:47], v[220:223], v[10:13], v[32:47]
	ds_read_b128 v[220:223], v217 offset:39488
	s_waitcnt lgkmcnt(0)
	v_mfma_f32_32x32x16_bf16 v[32:47], v[220:223], v[6:9], v[32:47]
	ds_read_b128 v[220:223], v217 offset:39520
	s_waitcnt lgkmcnt(0)
	v_mfma_f32_32x32x16_bf16 v[32:47], v[220:223], v[2:5], v[32:47]
	ds_read_b128 v[220:223], v217 offset:44032
	s_waitcnt lgkmcnt(0)
	v_mfma_f32_32x32x16_bf16 v[48:63], v[220:223], v[128:131], v[48:63]
	ds_read_b128 v[220:223], v217 offset:44064
	s_waitcnt lgkmcnt(0)
	v_mfma_f32_32x32x16_bf16 v[48:63], v[220:223], v[10:13], v[48:63]
	ds_read_b128 v[220:223], v217 offset:44096
	s_waitcnt lgkmcnt(0)
	v_mfma_f32_32x32x16_bf16 v[48:63], v[220:223], v[6:9], v[48:63]
	ds_read_b128 v[220:223], v217 offset:44128
	s_waitcnt lgkmcnt(0)
	v_mfma_f32_32x32x16_bf16 v[48:63], v[220:223], v[2:5], v[48:63]
	ds_read_b128 v[220:223], v217 offset:48640
	s_waitcnt lgkmcnt(0)
	v_mfma_f32_32x32x16_bf16 v[64:79], v[220:223], v[128:131], v[64:79]
	ds_read_b128 v[128:131], v217 offset:48672
	s_waitcnt lgkmcnt(0)
	v_mfma_f32_32x32x16_bf16 v[64:79], v[128:131], v[10:13], v[64:79]
	ds_read_b128 v[10:13], v217 offset:48704
	s_waitcnt lgkmcnt(0)
	v_mfma_f32_32x32x16_bf16 v[64:79], v[10:13], v[6:9], v[64:79]
	ds_read_b128 v[6:9], v217 offset:48736
	s_waitcnt lgkmcnt(0)
; DI u16 f2bf(float x) { return (u16)(pk2bf(x, 0.f) & 0xffffu); }
; DI int crow(int i, int h) { return (i & 3) + 8 * (i >> 2) + 4 * h; }
; DI void phase_scan_c(int wv_, int vb_, int nvb_, char* ws_, const Ctx& p, char* smem, int half) {
;     ...
;       u16* op = O + ((size_t)b * SEQ + (size_t)(half * 32 + nc) * 64) * 1024 + hd * 128 + dv0 + c;
; #pragma unroll
;       for (int tb = 0; tb < 2; ++tb)
; #pragma unroll
;         for (int i = 0; i < 16; ++i) op[(size_t)(tb * 32 + crow(i, h)) * 1024] = f2bf(Oa[tb][i]);
;       __syncthreads();
	v_mfma_f32_32x32x16_bf16 v[64:79], v[6:9], v[2:5], v[64:79]
	v_lshl_add_u64 v[2:3], v[184:185], 0, s[16:17]
	v_add_co_u32_e32 v4, vcc, s52, v2
	v_lshl_add_u64 v[184:185], v[184:185], 0, s[96:97]
	s_nop 0
	v_addc_co_u32_e32 v5, vcc, 0, v3, vcc
	v_add_co_u32_e32 v6, vcc, s62, v2
	s_nop 1
	v_addc_co_u32_e32 v7, vcc, 0, v3, vcc
	global_store_short v[6:7], v0, off offset:-4096
	v_cvt_pk_bf16_f32 v0, v97, s0
	global_store_short v[4:5], v0, off offset:2048
	v_cvt_pk_bf16_f32 v0, v98, s0
	v_add_co_u32_e32 v4, vcc, s63, v2
	global_store_short v[6:7], v0, off
	v_cvt_pk_bf16_f32 v0, v99, s0
	v_addc_co_u32_e32 v5, vcc, 0, v3, vcc
	global_store_short v[6:7], v0, off offset:2048
	v_add_co_u32_e32 v6, vcc, s64, v2
	v_cvt_pk_bf16_f32 v0, v100, s0
	s_nop 0
	v_addc_co_u32_e32 v7, vcc, 0, v3, vcc
	global_store_short v[6:7], v0, off offset:-4096
	v_cvt_pk_bf16_f32 v0, v101, s0
	global_store_short v[4:5], v0, off offset:2048
	v_cvt_pk_bf16_f32 v0, v102, s0
	v_add_co_u32_e32 v4, vcc, s65, v2
	global_store_short v[6:7], v0, off
	v_cvt_pk_bf16_f32 v0, v103, s0
	v_addc_co_u32_e32 v5, vcc, 0, v3, vcc
	global_store_short v[6:7], v0, off offset:2048
	v_add_co_u32_e32 v6, vcc, s68, v2
	v_cvt_pk_bf16_f32 v0, v104, s0
	s_nop 0
	v_addc_co_u32_e32 v7, vcc, 0, v3, vcc
	global_store_short v[6:7], v0, off offset:-4096
	v_cvt_pk_bf16_f32 v0, v105, s0
	global_store_short v[4:5], v0, off offset:2048
	v_cvt_pk_bf16_f32 v0, v106, s0
	v_add_co_u32_e32 v4, vcc, s69, v2
	global_store_short v[6:7], v0, off
	v_cvt_pk_bf16_f32 v0, v107, s0
	v_addc_co_u32_e32 v5, vcc, 0, v3, vcc
	global_store_short v[6:7], v0, off offset:2048
	v_add_co_u32_e32 v6, vcc, s72, v2
	v_cvt_pk_bf16_f32 v0, v108, s0
	s_nop 0
	v_addc_co_u32_e32 v7, vcc, 0, v3, vcc
	global_store_short v[6:7], v0, off offset:-4096
	v_cvt_pk_bf16_f32 v0, v109, s0
	global_store_short v[4:5], v0, off offset:2048
	v_cvt_pk_bf16_f32 v0, v110, s0
	v_add_co_u32_e32 v4, vcc, s73, v2
	global_store_short v[6:7], v0, off
	v_cvt_pk_bf16_f32 v0, v111, s0
	v_addc_co_u32_e32 v5, vcc, 0, v3, vcc
	global_store_short v[6:7], v0, off offset:2048
	v_add_co_u32_e32 v6, vcc, s76, v2
	v_cvt_pk_bf16_f32 v0, v80, s0
	s_nop 0
	v_addc_co_u32_e32 v7, vcc, 0, v3, vcc
	global_store_short v[6:7], v0, off offset:-4096
	v_cvt_pk_bf16_f32 v0, v81, s0
	global_store_short v[4:5], v0, off offset:2048
	v_cvt_pk_bf16_f32 v0, v82, s0
	v_add_co_u32_e32 v4, vcc, s77, v2
	global_store_short v[6:7], v0, off
	v_cvt_pk_bf16_f32 v0, v83, s0
	v_addc_co_u32_e32 v5, vcc, 0, v3, vcc
	global_store_short v[6:7], v0, off offset:2048
	v_add_co_u32_e32 v6, vcc, s88, v2
	v_cvt_pk_bf16_f32 v0, v84, s0
	s_nop 0
	v_addc_co_u32_e32 v7, vcc, 0, v3, vcc
	global_store_short v[6:7], v0, off offset:-4096
	v_cvt_pk_bf16_f32 v0, v85, s0
	global_store_short v[4:5], v0, off offset:2048
	v_cvt_pk_bf16_f32 v0, v86, s0
	v_add_co_u32_e32 v4, vcc, s89, v2
	global_store_short v[6:7], v0, off
	v_cvt_pk_bf16_f32 v0, v87, s0
	v_addc_co_u32_e32 v5, vcc, 0, v3, vcc
	global_store_short v[6:7], v0, off offset:2048
	v_add_co_u32_e32 v6, vcc, s90, v2
	v_cvt_pk_bf16_f32 v0, v88, s0
	s_nop 0
	v_addc_co_u32_e32 v7, vcc, 0, v3, vcc
	global_store_short v[6:7], v0, off offset:-4096
	v_cvt_pk_bf16_f32 v0, v89, s0
	global_store_short v[4:5], v0, off offset:2048
	v_add_co_u32_e32 v4, vcc, s91, v2
	v_cvt_pk_bf16_f32 v0, v90, s0
	s_nop 0
	v_addc_co_u32_e32 v5, vcc, 0, v3, vcc
	global_store_short v[6:7], v0, off
	v_cvt_pk_bf16_f32 v0, v91, s0
	v_add_co_u32_e32 v2, vcc, s94, v2
	global_store_short v[6:7], v0, off offset:2048
	v_cvt_pk_bf16_f32 v0, v92, s0
	v_addc_co_u32_e32 v3, vcc, 0, v3, vcc
	global_store_short v[2:3], v0, off offset:-4096
	v_cvt_pk_bf16_f32 v0, v93, s0
	global_store_short v[4:5], v0, off offset:2048
	v_cvt_pk_bf16_f32 v0, v94, s0
	v_cmp_eq_u32_e32 vcc, 0, v218
	global_store_short v[2:3], v0, off
	v_cvt_pk_bf16_f32 v0, v95, s0
	s_and_b64 vcc, exec, vcc
	global_store_short v[2:3], v0, off offset:2048
	s_barrier
; DI void phase_scan_c(int wv_, int vb_, int nvb_, char* ws_, const Ctx& p, char* smem, int half) {
;     ...
;       __syncthreads();
;       SWRITE()
;       __syncthreads();
;     }
;     ...
;     if (half == 0) {
; #pragma unroll
;       for (int mb = 0; mb < 4; ++mb)
; #pragma unroll
;         for (int i = 0; i < 16; ++i) stp[(mb * 16 + i) * 64] = S[mb][i];
;     }
	s_waitcnt vmcnt(43)
	ds_write_b128 v176, v[112:115]
	s_waitcnt vmcnt(42)
	ds_write_b128 v176, v[116:119] offset:17408
	s_waitcnt vmcnt(41)
	ds_write_b128 v177, v[120:123] offset:34816
	s_waitcnt vmcnt(40)
	ds_write_b128 v178, v[124:127]
	s_waitcnt vmcnt(39)
	ds_write_b128 v178, v[132:135] offset:17408
	s_waitcnt vmcnt(38)
	ds_write_b128 v179, v[136:139] offset:34816
	s_waitcnt vmcnt(37)
	ds_write_b128 v180, v[140:143]
	s_waitcnt vmcnt(36)
	ds_write_b128 v180, v[144:147] offset:17408
	s_waitcnt vmcnt(35)
	ds_write_b128 v181, v[148:151] offset:34816
	ds_write_b128 v182, v[152:155]
	s_waitcnt vmcnt(34)
	ds_write_b128 v182, v[156:159] offset:17408
	ds_write_b128 v183, v[160:163] offset:34816
	s_waitcnt vmcnt(33)
	ds_write_b128 v202, v[164:167] offset:53248
	s_waitcnt vmcnt(32)
	ds_write_b128 v203, v[168:171] offset:53248
	s_waitcnt lgkmcnt(0)
	s_barrier
	s_cbranch_vccz .LBB0_232
	s_waitcnt vmcnt(0)
	s_barrier
	s_mov_b32 s52, 0x6600000
	s_andn2_b64 vcc, exec, s[60:61]
	s_cbranch_vccnz .LBB0_235
	s_movk_i32 s0, 0x1000
	v_add_co_u32_e32 v2, vcc, s0, v172
	s_movk_i32 s0, 0x2000
	s_nop 0
	v_addc_co_u32_e32 v3, vcc, 0, v173, vcc
	v_add_co_u32_e32 v4, vcc, s0, v172
	s_movk_i32 s0, 0x3000
	s_nop 0
	v_addc_co_u32_e32 v5, vcc, 0, v173, vcc
	global_store_dword v[172:173], v16, off
	global_store_dword v[172:173], v17, off offset:256
	global_store_dword v[172:173], v18, off offset:512
	global_store_dword v[172:173], v19, off offset:768
	global_store_dword v[172:173], v20, off offset:1024
	global_store_dword v[172:173], v21, off offset:1280
	global_store_dword v[172:173], v22, off offset:1536
	global_store_dword v[172:173], v23, off offset:1792
	global_store_dword v[172:173], v24, off offset:2048
	global_store_dword v[172:173], v25, off offset:2304
	global_store_dword v[172:173], v26, off offset:2560
	global_store_dword v[172:173], v27, off offset:2816
	global_store_dword v[172:173], v28, off offset:3072
	global_store_dword v[172:173], v29, off offset:3328
	global_store_dword v[172:173], v30, off offset:3584
	global_store_dword v[172:173], v31, off offset:3840
	global_store_dword v[4:5], v32, off offset:-4096
	global_store_dword v[2:3], v33, off offset:256
	global_store_dword v[2:3], v34, off offset:512
	global_store_dword v[2:3], v35, off offset:768
	global_store_dword v[2:3], v36, off offset:1024
	global_store_dword v[2:3], v37, off offset:1280
	global_store_dword v[2:3], v38, off offset:1536
	global_store_dword v[2:3], v39, off offset:1792
	global_store_dword v[2:3], v40, off offset:2048
	global_store_dword v[2:3], v41, off offset:2304
	global_store_dword v[2:3], v42, off offset:2560
	global_store_dword v[2:3], v43, off offset:2816
	global_store_dword v[2:3], v44, off offset:3072
	global_store_dword v[2:3], v45, off offset:3328
	global_store_dword v[2:3], v46, off offset:3584
	global_store_dword v[2:3], v47, off offset:3840
	global_store_dword v[4:5], v48, off
	global_store_dword v[4:5], v49, off offset:256
	global_store_dword v[4:5], v50, off offset:512
	global_store_dword v[4:5], v51, off offset:768
	global_store_dword v[4:5], v52, off offset:1024
	global_store_dword v[4:5], v53, off offset:1280
	global_store_dword v[4:5], v54, off offset:1536
	global_store_dword v[4:5], v55, off offset:1792
	global_store_dword v[4:5], v56, off offset:2048
	global_store_dword v[4:5], v57, off offset:2304
	global_store_dword v[4:5], v58, off offset:2560
	global_store_dword v[4:5], v59, off offset:2816
	global_store_dword v[4:5], v60, off offset:3072
	global_store_dword v[4:5], v61, off offset:3328
	global_store_dword v[4:5], v62, off offset:3584
	global_store_dword v[4:5], v63, off offset:3840
	v_add_co_u32_e32 v2, vcc, s0, v172
	s_nop 1
	v_addc_co_u32_e32 v3, vcc, 0, v173, vcc
	global_store_dword v[2:3], v64, off
	global_store_dword v[2:3], v65, off offset:256
	global_store_dword v[2:3], v66, off offset:512
	global_store_dword v[2:3], v67, off offset:768
	global_store_dword v[2:3], v68, off offset:1024
	global_store_dword v[2:3], v69, off offset:1280
	global_store_dword v[2:3], v70, off offset:1536
	global_store_dword v[2:3], v71, off offset:1792
	global_store_dword v[2:3], v72, off offset:2048
	global_store_dword v[2:3], v73, off offset:2304
	global_store_dword v[2:3], v74, off offset:2560
	global_store_dword v[2:3], v75, off offset:2816
	global_store_dword v[2:3], v76, off offset:3072
	global_store_dword v[2:3], v77, off offset:3328
	global_store_dword v[2:3], v78, off offset:3584
	global_store_dword v[2:3], v79, off offset:3840
	s_branch .LBB0_235
